# GEMM compute segments: s_setprio 1 moved before the opening barrier, s_setprio 0 after the closing barrier, redundant lgkmcnt(0) and mid-block prio flips removed (no issue slots between barrier and MF
# speedup vs baseline: 1.0140x; 1.0064x over previous
; #define PG8_STAGE(bufoff, gbase, voff) do { _Pragma("unroll") for (int _i = 0; _i < 2; ++_i) \
;         __builtin_amdgcn_global_load_lds((const unsigned*)((const char*)(gbase) + (voff)[_i]), (PG8_LAS unsigned*)(lds + (bufoff) + ldsw + _i * 8192), 16, 0, 0); } while (0)
; #define PG8_LDA(dst, b, h) do { _Pragma("unroll") for (int m = 0; m < 4; ++m) _Pragma("unroll") for (int k = 0; k < 2; ++k) dst[m][k] = *(const PG8_LAS bf16x8*)(lds + PG8_SA(b, h) + aoff + m * 2048 + k * 1024); } while (0)
; #define PG8_LDB(dst, b, h) do { _Pragma("unroll") for (int n = 0; n < 2; ++n) _Pragma("unroll") for (int k = 0; k < 2; ++k) dst[n][k] = *(const PG8_LAS bf16x8*)(lds + PG8_SB(b, h) + boff + n * 2048 + k * 1024); } while (0)
; #define PG8_MMA(ai, bj, At, Bt) do { __builtin_amdgcn_s_setprio(1); _Pragma("unroll") for (int m = 0; m < 4; ++m) _Pragma("unroll") for (int n = 0; n < 2; ++n) _Pragma("unroll") for (int k = 0; k < 2; ++k) \
;         acc[ai][bj][m][n] = __builtin_amdgcn_mfma_f32_16x16x32_bf16(Bt[n][k], At[m][k], acc[ai][bj][m][n], 0, 0, 0); __builtin_amdgcn_s_setprio(0); } while (0)
; #define PG8_WAIT_V(n) asm volatile("s_waitcnt vmcnt(" #n ")" ::: "memory")
; #define PG8_WAIT_L(n) asm volatile("s_waitcnt lgkmcnt(" #n ")" ::: "memory")
; #define PG8_BAR __builtin_amdgcn_s_barrier()
; #define PG8_SCHED __builtin_amdgcn_sched_barrier(0)
; template <class Epi, class Sched, bool ALIGN_EPI = false, bool SP2 = false>
; __device__ __forceinline__ void gemm_phase(PG8_LAS unsigned char* lds, const Gemm g, const Sched& S, const Epi& E) {
;     ...
;             PG8_LDB(B0, 0, 0); PG8_LDB(B1, 0, 1); PG8_SCHED; PG8_LDA(At, 0, 0); PG8_STAGE(PG8_SA(1, 1), a1 + hstep, voffA);
;             PG8_WAIT_V(8); PG8_WAIT_L(0); PG8_BAR; PG8_MMA(0, 0, At, B0); PG8_MMA(0, 1, At, B1); PG8_BAR; PG8_SCHED;
;             PG8_LDA(At, 0, 1); PG8_STAGE(PG8_SB(0, 0), b2, voffB); PG8_STAGE(PG8_SB(0, 1), b2 + hstep, voffB); PG8_STAGE(PG8_SA(0, 0), a2, voffA);
;             PG8_WAIT_V(8); PG8_WAIT_L(0); PG8_BAR; PG8_MMA(1, 0, At, B0); PG8_MMA(1, 1, At, B1); PG8_BAR; PG8_SCHED;
.LBB0_232:
	s_add_u32 s20, s20, 0x80
	s_addc_u32 s21, s21, 0
	s_add_u32 s54, s22, 0x100
	s_addc_u32 s55, s23, 0
	s_mov_b32 s22, 0
	s_add_i32 s56, s22, 2
	s_add_u32 s57, s20, 0x80
	s_addc_u32 s23, s21, 0
	s_add_i32 s64, 0, 0x10000
	s_cmp_eq_u32 s43, s22
	s_cselect_b32 s23, s9, s23
	s_cselect_b32 s22, s8, s57
	v_add_u32_e32 v175, s64, v172
	s_cselect_b32 s59, s19, s55
	s_cselect_b32 s58, s18, s54
	s_add_i32 s57, 0, 0x14000
	ds_read_b128 v[176:179], v175
	ds_read_b128 v[180:183], v175 offset:1024
	ds_read_b128 v[184:187], v175 offset:2048
	ds_read_b128 v[188:191], v175 offset:3072
	v_add_u32_e32 v175, s57, v172
	ds_read_b128 v[192:195], v175
	ds_read_b128 v[196:199], v175 offset:1024
	ds_read_b128 v[200:203], v175 offset:2048
	ds_read_b128 v[204:207], v175 offset:3072
	v_lshl_add_u64 v[240:241], s[20:21], 0, v[150:151]
	s_add_i32 m0, s35, 0xc000
	ds_read_b128 v[208:211], v174
	ds_read_b128 v[212:215], v174 offset:1024
	ds_read_b128 v[216:219], v174 offset:2048
	ds_read_b128 v[220:223], v174 offset:3072
	ds_read_b128 v[224:227], v174 offset:4096
	ds_read_b128 v[228:231], v174 offset:5120
	ds_read_b128 v[232:235], v174 offset:6144
	ds_read_b128 v[236:239], v174 offset:7168
	global_load_lds_dwordx4 v[240:241], off
	v_lshl_add_u64 v[240:241], s[20:21], 0, v[152:153]
	s_add_i32 m0, s35, 0xe000
	s_nop 0
	global_load_lds_dwordx4 v[240:241], off
	s_waitcnt vmcnt(8)
	s_waitcnt lgkmcnt(0)
	s_setprio 1
	s_barrier
	v_mfma_f32_16x16x32_bf16 v[126:129], v[176:179], v[208:211], 0
	v_mfma_f32_16x16x32_bf16 v[122:125], v[184:187], v[208:211], 0
	v_mfma_f32_16x16x32_bf16 v[118:121], v[176:179], v[216:219], 0
	v_mfma_f32_16x16x32_bf16 v[114:117], v[184:187], v[216:219], 0
	v_mfma_f32_16x16x32_bf16 v[102:105], v[176:179], v[224:227], 0
	v_mfma_f32_16x16x32_bf16 v[98:101], v[184:187], v[224:227], 0
	v_mfma_f32_16x16x32_bf16 v[86:89], v[176:179], v[232:235], 0
	v_mfma_f32_16x16x32_bf16 v[82:85], v[184:187], v[232:235], 0
	v_mfma_f32_16x16x32_bf16 v[126:129], v[180:183], v[212:215], v[126:129]
	v_mfma_f32_16x16x32_bf16 v[122:125], v[188:191], v[212:215], v[122:125]
	v_mfma_f32_16x16x32_bf16 v[118:121], v[180:183], v[220:223], v[118:121]
	v_mfma_f32_16x16x32_bf16 v[114:117], v[188:191], v[220:223], v[114:117]
	v_mfma_f32_16x16x32_bf16 v[102:105], v[180:183], v[228:231], v[102:105]
	v_mfma_f32_16x16x32_bf16 v[98:101], v[188:191], v[228:231], v[98:101]
	v_mfma_f32_16x16x32_bf16 v[86:89], v[180:183], v[236:239], v[86:89]
	v_mfma_f32_16x16x32_bf16 v[82:85], v[188:191], v[236:239], v[82:85]
	v_mfma_f32_16x16x32_bf16 v[110:113], v[192:195], v[208:211], 0
	v_mfma_f32_16x16x32_bf16 v[106:109], v[200:203], v[208:211], 0
	v_mfma_f32_16x16x32_bf16 v[94:97], v[192:195], v[216:219], 0
	v_mfma_f32_16x16x32_bf16 v[90:93], v[200:203], v[216:219], 0
	v_mfma_f32_16x16x32_bf16 v[78:81], v[192:195], v[224:227], 0
	v_mfma_f32_16x16x32_bf16 v[74:77], v[200:203], v[224:227], 0
	v_mfma_f32_16x16x32_bf16 v[70:73], v[192:195], v[232:235], 0
	v_mfma_f32_16x16x32_bf16 v[66:69], v[200:203], v[232:235], 0
	v_mfma_f32_16x16x32_bf16 v[110:113], v[196:199], v[212:215], v[110:113]
	v_mfma_f32_16x16x32_bf16 v[106:109], v[204:207], v[212:215], v[106:109]
	v_mfma_f32_16x16x32_bf16 v[94:97], v[196:199], v[220:223], v[94:97]
	v_mfma_f32_16x16x32_bf16 v[90:93], v[204:207], v[220:223], v[90:93]
	v_mfma_f32_16x16x32_bf16 v[78:81], v[196:199], v[228:231], v[78:81]
	v_mfma_f32_16x16x32_bf16 v[74:77], v[204:207], v[228:231], v[74:77]
	v_mfma_f32_16x16x32_bf16 v[70:73], v[196:199], v[236:239], v[70:73]
	v_mfma_f32_16x16x32_bf16 v[66:69], v[204:207], v[236:239], v[66:69]
	s_barrier
	s_setprio 0
	s_add_i32 s64, s64, s28
	v_lshl_add_u64 v[240:241], s[58:59], 0, v[0:1]
	s_mov_b32 m0, s64
	ds_read_b128 v[208:211], v174 offset:16384
	ds_read_b128 v[212:215], v174 offset:17408
	ds_read_b128 v[216:219], v174 offset:18432
	ds_read_b128 v[220:223], v174 offset:19456
	ds_read_b128 v[224:227], v174 offset:20480
	ds_read_b128 v[228:231], v174 offset:21504
	ds_read_b128 v[232:235], v174 offset:22528
	ds_read_b128 v[236:239], v174 offset:23552
	global_load_lds_dwordx4 v[240:241], off
	s_add_i32 m0, s64, 0x2000
	v_lshl_add_u64 v[242:243], s[58:59], 0, v[144:145]
	s_add_u32 s58, s58, s62
	s_addc_u32 s59, s59, 0
	s_add_i32 s57, s57, s28
	global_load_lds_dwordx4 v[242:243], off
	v_lshl_add_u64 v[244:245], s[58:59], 0, v[0:1]
	s_mov_b32 m0, s57
	v_lshl_add_u64 v[246:247], s[58:59], 0, v[144:145]
	global_load_lds_dwordx4 v[244:245], off
	s_add_i32 m0, s57, 0x2000
	v_lshl_add_u64 v[248:249], s[22:23], 0, v[148:149]
	global_load_lds_dwordx4 v[246:247], off
	s_mov_b32 m0, s35
	v_lshl_add_u64 v[250:251], s[22:23], 0, v[146:147]
	global_load_lds_dwordx4 v[248:249], off
	s_mov_b32 m0, s36
	s_nop 0
	global_load_lds_dwordx4 v[250:251], off
	s_waitcnt vmcnt(8)
	s_waitcnt lgkmcnt(0)
	s_setprio 1
	s_barrier
; #define PG8_STAGE(bufoff, gbase, voff) do { _Pragma("unroll") for (int _i = 0; _i < 2; ++_i) \
;         __builtin_amdgcn_global_load_lds((const unsigned*)((const char*)(gbase) + (voff)[_i]), (PG8_LAS unsigned*)(lds + (bufoff) + ldsw + _i * 8192), 16, 0, 0); } while (0)
; #define PG8_LDA(dst, b, h) do { _Pragma("unroll") for (int m = 0; m < 4; ++m) _Pragma("unroll") for (int k = 0; k < 2; ++k) dst[m][k] = *(const PG8_LAS bf16x8*)(lds + PG8_SA(b, h) + aoff + m * 2048 + k * 1024); } while (0)
; #define PG8_LDB(dst, b, h) do { _Pragma("unroll") for (int n = 0; n < 2; ++n) _Pragma("unroll") for (int k = 0; k < 2; ++k) dst[n][k] = *(const PG8_LAS bf16x8*)(lds + PG8_SB(b, h) + boff + n * 2048 + k * 1024); } while (0)
; #define PG8_MMA(ai, bj, At, Bt) do { __builtin_amdgcn_s_setprio(1); _Pragma("unroll") for (int m = 0; m < 4; ++m) _Pragma("unroll") for (int n = 0; n < 2; ++n) _Pragma("unroll") for (int k = 0; k < 2; ++k) \
;         acc[ai][bj][m][n] = __builtin_amdgcn_mfma_f32_16x16x32_bf16(Bt[n][k], At[m][k], acc[ai][bj][m][n], 0, 0, 0); __builtin_amdgcn_s_setprio(0); } while (0)
; #define PG8_WAIT_V(n) asm volatile("s_waitcnt vmcnt(" #n ")" ::: "memory")
; #define PG8_WAIT_L(n) asm volatile("s_waitcnt lgkmcnt(" #n ")" ::: "memory")
; #define PG8_BAR __builtin_amdgcn_s_barrier()
; #define PG8_SCHED __builtin_amdgcn_sched_barrier(0)
; template <class Epi, class Sched, bool ALIGN_EPI = false, bool SP2 = false>
; __device__ __forceinline__ void gemm_phase(PG8_LAS unsigned char* lds, const Gemm g, const Sched& S, const Epi& E) {
;     ...
;             PG8_WAIT_V(8); PG8_WAIT_L(0); PG8_BAR; PG8_MMA(1, 0, At, B0); PG8_MMA(1, 1, At, B1); PG8_BAR; PG8_SCHED;
;             PG8_LDB(B0, 1, 0); PG8_LDB(B1, 1, 1); PG8_SCHED; PG8_LDA(At, 1, 0); PG8_STAGE(PG8_SA(0, 1), a2 + hstep, voffA);
;             PG8_WAIT_V(8); PG8_WAIT_L(0); PG8_BAR; PG8_MMA(0, 0, At, B0); PG8_MMA(0, 1, At, B1); PG8_BAR; PG8_SCHED;
	v_mfma_f32_16x16x32_bf16 v[62:65], v[176:179], v[208:211], 0
	v_mfma_f32_16x16x32_bf16 v[58:61], v[184:187], v[208:211], 0
	v_mfma_f32_16x16x32_bf16 v[54:57], v[176:179], v[216:219], 0
	v_mfma_f32_16x16x32_bf16 v[50:53], v[184:187], v[216:219], 0
	v_mfma_f32_16x16x32_bf16 v[38:41], v[176:179], v[224:227], 0
	v_mfma_f32_16x16x32_bf16 v[34:37], v[184:187], v[224:227], 0
	v_mfma_f32_16x16x32_bf16 v[22:25], v[176:179], v[232:235], 0
	v_mfma_f32_16x16x32_bf16 v[18:21], v[184:187], v[232:235], 0
	v_mfma_f32_16x16x32_bf16 v[62:65], v[180:183], v[212:215], v[62:65]
	v_mfma_f32_16x16x32_bf16 v[58:61], v[188:191], v[212:215], v[58:61]
	v_mfma_f32_16x16x32_bf16 v[54:57], v[180:183], v[220:223], v[54:57]
	v_mfma_f32_16x16x32_bf16 v[50:53], v[188:191], v[220:223], v[50:53]
	v_mfma_f32_16x16x32_bf16 v[38:41], v[180:183], v[228:231], v[38:41]
	v_mfma_f32_16x16x32_bf16 v[34:37], v[188:191], v[228:231], v[34:37]
	v_mfma_f32_16x16x32_bf16 v[22:25], v[180:183], v[236:239], v[22:25]
	v_mfma_f32_16x16x32_bf16 v[18:21], v[188:191], v[236:239], v[18:21]
	v_mfma_f32_16x16x32_bf16 v[46:49], v[192:195], v[208:211], 0
	v_mfma_f32_16x16x32_bf16 v[42:45], v[200:203], v[208:211], 0
	v_mfma_f32_16x16x32_bf16 v[30:33], v[192:195], v[216:219], 0
	v_mfma_f32_16x16x32_bf16 v[26:29], v[200:203], v[216:219], 0
	v_mfma_f32_16x16x32_bf16 v[14:17], v[192:195], v[224:227], 0
	v_mfma_f32_16x16x32_bf16 v[10:13], v[200:203], v[224:227], 0
	v_mfma_f32_16x16x32_bf16 v[6:9], v[192:195], v[232:235], 0
	v_mfma_f32_16x16x32_bf16 v[2:5], v[200:203], v[232:235], 0
	v_mfma_f32_16x16x32_bf16 v[46:49], v[196:199], v[212:215], v[46:49]
	v_mfma_f32_16x16x32_bf16 v[42:45], v[204:207], v[212:215], v[42:45]
	v_mfma_f32_16x16x32_bf16 v[30:33], v[196:199], v[220:223], v[30:33]
	v_mfma_f32_16x16x32_bf16 v[26:29], v[204:207], v[220:223], v[26:29]
	v_mfma_f32_16x16x32_bf16 v[14:17], v[196:199], v[228:231], v[14:17]
	v_mfma_f32_16x16x32_bf16 v[10:13], v[204:207], v[228:231], v[10:13]
	v_mfma_f32_16x16x32_bf16 v[6:9], v[196:199], v[236:239], v[6:9]
	v_mfma_f32_16x16x32_bf16 v[2:5], v[204:207], v[236:239], v[2:5]
	s_barrier
	s_setprio 0
	s_add_i32 s57, 0, 0x18000
	v_add_u32_e32 v175, s57, v172
	s_add_i32 s58, 0, 0x1c000
	ds_read_b128 v[176:179], v175
	ds_read_b128 v[180:183], v175 offset:1024
	ds_read_b128 v[184:187], v175 offset:2048
	ds_read_b128 v[188:191], v175 offset:3072
	v_add_u32_e32 v175, s58, v172
	ds_read_b128 v[192:195], v175
	ds_read_b128 v[196:199], v175 offset:1024
	ds_read_b128 v[200:203], v175 offset:2048
	ds_read_b128 v[204:207], v175 offset:3072
	s_add_u32 s22, s22, s62
	s_addc_u32 s23, s23, 0
	s_mov_b32 m0, s37
	v_lshl_add_u64 v[252:253], s[22:23], 0, v[148:149]
	ds_read_b128 v[208:211], v174 offset:32768
	ds_read_b128 v[212:215], v174 offset:33792
	ds_read_b128 v[216:219], v174 offset:34816
	ds_read_b128 v[220:223], v174 offset:35840
	ds_read_b128 v[224:227], v174 offset:36864
	ds_read_b128 v[228:231], v174 offset:37888
	ds_read_b128 v[232:235], v174 offset:38912
	ds_read_b128 v[236:239], v174 offset:39936
	global_load_lds_dwordx4 v[252:253], off
	v_lshl_add_u64 v[252:253], s[22:23], 0, v[146:147]
	s_mov_b32 m0, s38
	s_nop 0
	global_load_lds_dwordx4 v[252:253], off
	s_waitcnt vmcnt(8)
	s_waitcnt lgkmcnt(0)
	s_setprio 1
	s_barrier
	v_mfma_f32_16x16x32_bf16 v[126:129], v[176:179], v[208:211], v[126:129]
	v_mfma_f32_16x16x32_bf16 v[122:125], v[184:187], v[208:211], v[122:125]
	v_mfma_f32_16x16x32_bf16 v[118:121], v[176:179], v[216:219], v[118:121]
	v_mfma_f32_16x16x32_bf16 v[114:117], v[184:187], v[216:219], v[114:117]
	v_mfma_f32_16x16x32_bf16 v[102:105], v[176:179], v[224:227], v[102:105]
	v_mfma_f32_16x16x32_bf16 v[98:101], v[184:187], v[224:227], v[98:101]
	v_mfma_f32_16x16x32_bf16 v[86:89], v[176:179], v[232:235], v[86:89]
	v_mfma_f32_16x16x32_bf16 v[82:85], v[184:187], v[232:235], v[82:85]
	v_mfma_f32_16x16x32_bf16 v[126:129], v[180:183], v[212:215], v[126:129]
	v_mfma_f32_16x16x32_bf16 v[122:125], v[188:191], v[212:215], v[122:125]
	v_mfma_f32_16x16x32_bf16 v[118:121], v[180:183], v[220:223], v[118:121]
	v_mfma_f32_16x16x32_bf16 v[114:117], v[188:191], v[220:223], v[114:117]
	v_mfma_f32_16x16x32_bf16 v[102:105], v[180:183], v[228:231], v[102:105]
	v_mfma_f32_16x16x32_bf16 v[98:101], v[188:191], v[228:231], v[98:101]
	v_mfma_f32_16x16x32_bf16 v[86:89], v[180:183], v[236:239], v[86:89]
	v_mfma_f32_16x16x32_bf16 v[82:85], v[188:191], v[236:239], v[82:85]
	v_mfma_f32_16x16x32_bf16 v[110:113], v[192:195], v[208:211], v[110:113]
	v_mfma_f32_16x16x32_bf16 v[106:109], v[200:203], v[208:211], v[106:109]
	v_mfma_f32_16x16x32_bf16 v[94:97], v[192:195], v[216:219], v[94:97]
	v_mfma_f32_16x16x32_bf16 v[90:93], v[200:203], v[216:219], v[90:93]
	v_mfma_f32_16x16x32_bf16 v[78:81], v[192:195], v[224:227], v[78:81]
	v_mfma_f32_16x16x32_bf16 v[74:77], v[200:203], v[224:227], v[74:77]
	v_mfma_f32_16x16x32_bf16 v[70:73], v[192:195], v[232:235], v[70:73]
	v_mfma_f32_16x16x32_bf16 v[66:69], v[200:203], v[232:235], v[66:69]
	v_mfma_f32_16x16x32_bf16 v[110:113], v[196:199], v[212:215], v[110:113]
	v_mfma_f32_16x16x32_bf16 v[106:109], v[204:207], v[212:215], v[106:109]
	v_mfma_f32_16x16x32_bf16 v[94:97], v[196:199], v[220:223], v[94:97]
	v_mfma_f32_16x16x32_bf16 v[90:93], v[204:207], v[220:223], v[90:93]
	v_mfma_f32_16x16x32_bf16 v[78:81], v[196:199], v[228:231], v[78:81]
	v_mfma_f32_16x16x32_bf16 v[74:77], v[204:207], v[228:231], v[74:77]
	v_mfma_f32_16x16x32_bf16 v[70:73], v[196:199], v[236:239], v[70:73]
	v_mfma_f32_16x16x32_bf16 v[66:69], v[204:207], v[236:239], v[66:69]
	s_barrier
; #define PG8_STAGE(bufoff, gbase, voff) do { _Pragma("unroll") for (int _i = 0; _i < 2; ++_i) \
;         __builtin_amdgcn_global_load_lds((const unsigned*)((const char*)(gbase) + (voff)[_i]), (PG8_LAS unsigned*)(lds + (bufoff) + ldsw + _i * 8192), 16, 0, 0); } while (0)
; #define PG8_LDA(dst, b, h) do { _Pragma("unroll") for (int m = 0; m < 4; ++m) _Pragma("unroll") for (int k = 0; k < 2; ++k) dst[m][k] = *(const PG8_LAS bf16x8*)(lds + PG8_SA(b, h) + aoff + m * 2048 + k * 1024); } while (0)
; #define PG8_LDB(dst, b, h) do { _Pragma("unroll") for (int n = 0; n < 2; ++n) _Pragma("unroll") for (int k = 0; k < 2; ++k) dst[n][k] = *(const PG8_LAS bf16x8*)(lds + PG8_SB(b, h) + boff + n * 2048 + k * 1024); } while (0)
; template <class Epi, class Sched, bool ALIGN_EPI = false, bool SP2 = false>
; __device__ __forceinline__ void gemm_phase(PG8_LAS unsigned char* lds, const Gemm g, const Sched& S, const Epi& E) {
;     ...
;         for (int t = 0; t < nt; t += 2) {
;             const bool last = (t == nt - 2);
;             const char* a1 = cA + (size_t)(t + 1) * kstep;
;             const char* a2 = last ? nA : cA + (size_t)(t + 2) * kstep; const char* b2 = last ? nB : cB + (size_t)(t + 2) * kstep;
;             const char* a3 = a2 + kstep; const char* b3 = b2 + kstep;
;             if (last && has_next) S.a_ready(nxt);
;             if constexpr (SP2) {
;             PG8_LDB(B0, 0, 0); PG8_LDB(B1, 0, 1); PG8_SCHED; PG8_LDA(At, 0, 0); PG8_STAGE(PG8_SA(1, 1), a1 + hstep, voffA);
;             PG8_WAIT_V(8); PG8_WAIT_L(0); PG8_BAR; PG8_MMA(0, 0, At, B0); PG8_MMA(0, 1, At, B1); PG8_BAR; PG8_SCHED;
;             PG8_LDA(At, 0, 1); PG8_STAGE(PG8_SB(0, 0), b2, voffB); PG8_STAGE(PG8_SB(0, 1), b2 + hstep, voffB); PG8_STAGE(PG8_SA(0, 0), a2, voffA);
;             PG8_WAIT_V(8); PG8_WAIT_L(0); PG8_BAR; PG8_MMA(1, 0, At, B0); PG8_MMA(1, 1, At, B1); PG8_BAR; PG8_SCHED;
;             PG8_LDB(B0, 1, 0); PG8_LDB(B1, 1, 1); PG8_SCHED; PG8_LDA(At, 1, 0); PG8_STAGE(PG8_SA(0, 1), a2 + hstep, voffA);
;             PG8_WAIT_V(8); PG8_WAIT_L(0); PG8_BAR; PG8_MMA(0, 0, At, B0); PG8_MMA(0, 1, At, B1); PG8_BAR; PG8_SCHED;
;             PG8_LDA(At, 1, 1); PG8_STAGE(PG8_SB(1, 0), b3, voffB); PG8_STAGE(PG8_SB(1, 1), b3 + hstep, voffB); PG8_STAGE(PG8_SA(1, 0), a3, voffA);
;             PG8_WAIT_V(8); PG8_WAIT_L(0); PG8_BAR; PG8_MMA(1, 0, At, B0); PG8_MMA(1, 1, At, B1); PG8_BAR; PG8_SCHED;
	s_setprio 0
	s_add_i32 s22, s57, s28
	v_lshl_add_u64 v[240:241], v[240:241], 0, s[86:87]
	s_mov_b32 m0, s22
	ds_read_b128 v[208:211], v174 offset:49152
	ds_read_b128 v[212:215], v174 offset:50176
	ds_read_b128 v[216:219], v174 offset:51200
	ds_read_b128 v[220:223], v174 offset:52224
	ds_read_b128 v[224:227], v174 offset:53248
	ds_read_b128 v[228:231], v174 offset:54272
	ds_read_b128 v[232:235], v174 offset:55296
	ds_read_b128 v[236:239], v174 offset:56320
	global_load_lds_dwordx4 v[240:241], off
	v_lshl_add_u64 v[240:241], v[242:243], 0, s[86:87]
	s_add_i32 m0, s22, 0x2000
	s_add_i32 s22, s58, s28
	global_load_lds_dwordx4 v[240:241], off
	v_lshl_add_u64 v[240:241], v[244:245], 0, s[86:87]
	s_mov_b32 m0, s22
	s_nop 0
	global_load_lds_dwordx4 v[240:241], off
	v_lshl_add_u64 v[240:241], v[246:247], 0, s[86:87]
	s_add_i32 m0, s22, 0x2000
	s_nop 0
	global_load_lds_dwordx4 v[240:241], off
	v_lshl_add_u64 v[240:241], v[248:249], 0, s[86:87]
	s_mov_b32 m0, s40
	s_nop 0
	global_load_lds_dwordx4 v[240:241], off
	v_lshl_add_u64 v[240:241], v[250:251], 0, s[86:87]
	s_mov_b32 m0, s41
	s_nop 0
	global_load_lds_dwordx4 v[240:241], off
	s_waitcnt vmcnt(8)
	s_waitcnt lgkmcnt(0)
	s_setprio 1
	s_barrier
	v_mfma_f32_16x16x32_bf16 v[62:65], v[176:179], v[208:211], v[62:65]
	v_mfma_f32_16x16x32_bf16 v[58:61], v[184:187], v[208:211], v[58:61]
	v_mfma_f32_16x16x32_bf16 v[54:57], v[176:179], v[216:219], v[54:57]
	v_mfma_f32_16x16x32_bf16 v[50:53], v[184:187], v[216:219], v[50:53]
	v_mfma_f32_16x16x32_bf16 v[38:41], v[176:179], v[224:227], v[38:41]
	v_mfma_f32_16x16x32_bf16 v[34:37], v[184:187], v[224:227], v[34:37]
	v_mfma_f32_16x16x32_bf16 v[22:25], v[176:179], v[232:235], v[22:25]
	v_mfma_f32_16x16x32_bf16 v[18:21], v[184:187], v[232:235], v[18:21]
	v_mfma_f32_16x16x32_bf16 v[62:65], v[180:183], v[212:215], v[62:65]
	v_mfma_f32_16x16x32_bf16 v[58:61], v[188:191], v[212:215], v[58:61]
	v_mfma_f32_16x16x32_bf16 v[54:57], v[180:183], v[220:223], v[54:57]
	v_mfma_f32_16x16x32_bf16 v[50:53], v[188:191], v[220:223], v[50:53]
	v_mfma_f32_16x16x32_bf16 v[38:41], v[180:183], v[228:231], v[38:41]
	v_mfma_f32_16x16x32_bf16 v[34:37], v[188:191], v[228:231], v[34:37]
	v_mfma_f32_16x16x32_bf16 v[22:25], v[180:183], v[236:239], v[22:25]
	v_mfma_f32_16x16x32_bf16 v[18:21], v[188:191], v[236:239], v[18:21]
	v_mfma_f32_16x16x32_bf16 v[46:49], v[192:195], v[208:211], v[46:49]
	v_mfma_f32_16x16x32_bf16 v[42:45], v[200:203], v[208:211], v[42:45]
	v_mfma_f32_16x16x32_bf16 v[30:33], v[192:195], v[216:219], v[30:33]
	v_mfma_f32_16x16x32_bf16 v[26:29], v[200:203], v[216:219], v[26:29]
	v_mfma_f32_16x16x32_bf16 v[14:17], v[192:195], v[224:227], v[14:17]
	v_mfma_f32_16x16x32_bf16 v[10:13], v[200:203], v[224:227], v[10:13]
	v_mfma_f32_16x16x32_bf16 v[6:9], v[192:195], v[232:235], v[6:9]
	v_mfma_f32_16x16x32_bf16 v[2:5], v[200:203], v[232:235], v[2:5]
	v_mfma_f32_16x16x32_bf16 v[46:49], v[196:199], v[212:215], v[46:49]
	v_mfma_f32_16x16x32_bf16 v[42:45], v[204:207], v[212:215], v[42:45]
	v_mfma_f32_16x16x32_bf16 v[30:33], v[196:199], v[220:223], v[30:33]
	v_mfma_f32_16x16x32_bf16 v[26:29], v[204:207], v[220:223], v[26:29]
	v_mfma_f32_16x16x32_bf16 v[14:17], v[196:199], v[228:231], v[14:17]
	v_mfma_f32_16x16x32_bf16 v[10:13], v[204:207], v[228:231], v[10:13]
	v_mfma_f32_16x16x32_bf16 v[6:9], v[196:199], v[236:239], v[6:9]
	v_mfma_f32_16x16x32_bf16 v[2:5], v[204:207], v[236:239], v[2:5]
	s_barrier
	s_setprio 0
	s_add_u32 s20, s20, 0x100
	s_addc_u32 s21, s21, 0
	s_add_u32 s54, s54, 0x100
	s_addc_u32 s55, s55, 0
	s_cmp_ge_u32 s56, s39
	s_mov_b32 s22, s56
	s_cbranch_scc1 .Lpeel_after_A
.LBB0_233:
	s_add_i32 s56, s22, 2
	s_add_u32 s57, s20, 0x80
	s_addc_u32 s23, s21, 0
	s_add_i32 s64, 0, 0x10000
	s_cmp_eq_u32 s43, s22
	s_cselect_b32 s23, s9, s23
	s_cselect_b32 s22, s8, s57
	v_add_u32_e32 v175, s64, v172
	s_cselect_b32 s59, s19, s55
	s_cselect_b32 s58, s18, s54
	s_add_i32 s57, 0, 0x14000
	ds_read_b128 v[176:179], v175
	ds_read_b128 v[180:183], v175 offset:1024
	ds_read_b128 v[184:187], v175 offset:2048
	ds_read_b128 v[188:191], v175 offset:3072
	v_add_u32_e32 v175, s57, v172
	ds_read_b128 v[192:195], v175
	ds_read_b128 v[196:199], v175 offset:1024
	ds_read_b128 v[200:203], v175 offset:2048
	ds_read_b128 v[204:207], v175 offset:3072
	v_lshl_add_u64 v[240:241], s[20:21], 0, v[150:151]
	s_add_i32 m0, s35, 0xc000
	ds_read_b128 v[208:211], v174
	ds_read_b128 v[212:215], v174 offset:1024
	ds_read_b128 v[216:219], v174 offset:2048
	ds_read_b128 v[220:223], v174 offset:3072
	ds_read_b128 v[224:227], v174 offset:4096
	ds_read_b128 v[228:231], v174 offset:5120
	ds_read_b128 v[232:235], v174 offset:6144
	ds_read_b128 v[236:239], v174 offset:7168
	global_load_lds_dwordx4 v[240:241], off
	v_lshl_add_u64 v[240:241], s[20:21], 0, v[152:153]
	s_add_i32 m0, s35, 0xe000
	s_nop 0
	global_load_lds_dwordx4 v[240:241], off
	s_waitcnt vmcnt(8)
	s_waitcnt lgkmcnt(0)
	s_setprio 1
	s_barrier
; #define PG8_STAGE(bufoff, gbase, voff) do { _Pragma("unroll") for (int _i = 0; _i < 2; ++_i) \
;         __builtin_amdgcn_global_load_lds((const unsigned*)((const char*)(gbase) + (voff)[_i]), (PG8_LAS unsigned*)(lds + (bufoff) + ldsw + _i * 8192), 16, 0, 0); } while (0)
; #define PG8_LDA(dst, b, h) do { _Pragma("unroll") for (int m = 0; m < 4; ++m) _Pragma("unroll") for (int k = 0; k < 2; ++k) dst[m][k] = *(const PG8_LAS bf16x8*)(lds + PG8_SA(b, h) + aoff + m * 2048 + k * 1024); } while (0)
; #define PG8_LDB(dst, b, h) do { _Pragma("unroll") for (int n = 0; n < 2; ++n) _Pragma("unroll") for (int k = 0; k < 2; ++k) dst[n][k] = *(const PG8_LAS bf16x8*)(lds + PG8_SB(b, h) + boff + n * 2048 + k * 1024); } while (0)
; #define PG8_MMA(ai, bj, At, Bt) do { __builtin_amdgcn_s_setprio(1); _Pragma("unroll") for (int m = 0; m < 4; ++m) _Pragma("unroll") for (int n = 0; n < 2; ++n) _Pragma("unroll") for (int k = 0; k < 2; ++k) \
;         acc[ai][bj][m][n] = __builtin_amdgcn_mfma_f32_16x16x32_bf16(Bt[n][k], At[m][k], acc[ai][bj][m][n], 0, 0, 0); __builtin_amdgcn_s_setprio(0); } while (0)
; #define PG8_WAIT_V(n) asm volatile("s_waitcnt vmcnt(" #n ")" ::: "memory")
; #define PG8_WAIT_L(n) asm volatile("s_waitcnt lgkmcnt(" #n ")" ::: "memory")
; #define PG8_BAR __builtin_amdgcn_s_barrier()
; #define PG8_SCHED __builtin_amdgcn_sched_barrier(0)
; template <class Epi, class Sched, bool ALIGN_EPI = false, bool SP2 = false>
; __device__ __forceinline__ void gemm_phase(PG8_LAS unsigned char* lds, const Gemm g, const Sched& S, const Epi& E) {
;     ...
;             PG8_LDB(B0, 0, 0); PG8_LDB(B1, 0, 1); PG8_SCHED; PG8_LDA(At, 0, 0); PG8_STAGE(PG8_SA(1, 1), a1 + hstep, voffA);
;             PG8_WAIT_V(8); PG8_WAIT_L(0); PG8_BAR; PG8_MMA(0, 0, At, B0); PG8_MMA(0, 1, At, B1); PG8_BAR; PG8_SCHED;
;             PG8_LDA(At, 0, 1); PG8_STAGE(PG8_SB(0, 0), b2, voffB); PG8_STAGE(PG8_SB(0, 1), b2 + hstep, voffB); PG8_STAGE(PG8_SA(0, 0), a2, voffA);
;             PG8_WAIT_V(8); PG8_WAIT_L(0); PG8_BAR; PG8_MMA(1, 0, At, B0); PG8_MMA(1, 1, At, B1); PG8_BAR; PG8_SCHED;
	v_mfma_f32_16x16x32_bf16 v[126:129], v[176:179], v[208:211], v[126:129]
	v_mfma_f32_16x16x32_bf16 v[122:125], v[184:187], v[208:211], v[122:125]
	v_mfma_f32_16x16x32_bf16 v[118:121], v[176:179], v[216:219], v[118:121]
	v_mfma_f32_16x16x32_bf16 v[114:117], v[184:187], v[216:219], v[114:117]
	v_mfma_f32_16x16x32_bf16 v[102:105], v[176:179], v[224:227], v[102:105]
	v_mfma_f32_16x16x32_bf16 v[98:101], v[184:187], v[224:227], v[98:101]
	v_mfma_f32_16x16x32_bf16 v[86:89], v[176:179], v[232:235], v[86:89]
	v_mfma_f32_16x16x32_bf16 v[82:85], v[184:187], v[232:235], v[82:85]
	v_mfma_f32_16x16x32_bf16 v[126:129], v[180:183], v[212:215], v[126:129]
	v_mfma_f32_16x16x32_bf16 v[122:125], v[188:191], v[212:215], v[122:125]
	v_mfma_f32_16x16x32_bf16 v[118:121], v[180:183], v[220:223], v[118:121]
	v_mfma_f32_16x16x32_bf16 v[114:117], v[188:191], v[220:223], v[114:117]
	v_mfma_f32_16x16x32_bf16 v[102:105], v[180:183], v[228:231], v[102:105]
	v_mfma_f32_16x16x32_bf16 v[98:101], v[188:191], v[228:231], v[98:101]
	v_mfma_f32_16x16x32_bf16 v[86:89], v[180:183], v[236:239], v[86:89]
	v_mfma_f32_16x16x32_bf16 v[82:85], v[188:191], v[236:239], v[82:85]
	v_mfma_f32_16x16x32_bf16 v[110:113], v[192:195], v[208:211], v[110:113]
	v_mfma_f32_16x16x32_bf16 v[106:109], v[200:203], v[208:211], v[106:109]
	v_mfma_f32_16x16x32_bf16 v[94:97], v[192:195], v[216:219], v[94:97]
	v_mfma_f32_16x16x32_bf16 v[90:93], v[200:203], v[216:219], v[90:93]
	v_mfma_f32_16x16x32_bf16 v[78:81], v[192:195], v[224:227], v[78:81]
	v_mfma_f32_16x16x32_bf16 v[74:77], v[200:203], v[224:227], v[74:77]
	v_mfma_f32_16x16x32_bf16 v[70:73], v[192:195], v[232:235], v[70:73]
	v_mfma_f32_16x16x32_bf16 v[66:69], v[200:203], v[232:235], v[66:69]
	v_mfma_f32_16x16x32_bf16 v[110:113], v[196:199], v[212:215], v[110:113]
	v_mfma_f32_16x16x32_bf16 v[106:109], v[204:207], v[212:215], v[106:109]
	v_mfma_f32_16x16x32_bf16 v[94:97], v[196:199], v[220:223], v[94:97]
	v_mfma_f32_16x16x32_bf16 v[90:93], v[204:207], v[220:223], v[90:93]
	v_mfma_f32_16x16x32_bf16 v[78:81], v[196:199], v[228:231], v[78:81]
	v_mfma_f32_16x16x32_bf16 v[74:77], v[204:207], v[228:231], v[74:77]
	v_mfma_f32_16x16x32_bf16 v[70:73], v[196:199], v[236:239], v[70:73]
	v_mfma_f32_16x16x32_bf16 v[66:69], v[204:207], v[236:239], v[66:69]
	s_barrier
	s_setprio 0
	s_add_i32 s64, s64, s28
	v_lshl_add_u64 v[240:241], s[58:59], 0, v[0:1]
	s_mov_b32 m0, s64
	ds_read_b128 v[208:211], v174 offset:16384
	ds_read_b128 v[212:215], v174 offset:17408
	ds_read_b128 v[216:219], v174 offset:18432
	ds_read_b128 v[220:223], v174 offset:19456
	ds_read_b128 v[224:227], v174 offset:20480
	ds_read_b128 v[228:231], v174 offset:21504
	ds_read_b128 v[232:235], v174 offset:22528
	ds_read_b128 v[236:239], v174 offset:23552
	global_load_lds_dwordx4 v[240:241], off
	s_add_i32 m0, s64, 0x2000
	v_lshl_add_u64 v[242:243], s[58:59], 0, v[144:145]
	s_add_u32 s58, s58, s62
	s_addc_u32 s59, s59, 0
	s_add_i32 s57, s57, s28
	global_load_lds_dwordx4 v[242:243], off
	v_lshl_add_u64 v[244:245], s[58:59], 0, v[0:1]
	s_mov_b32 m0, s57
	v_lshl_add_u64 v[246:247], s[58:59], 0, v[144:145]
	global_load_lds_dwordx4 v[244:245], off
	s_add_i32 m0, s57, 0x2000
	v_lshl_add_u64 v[248:249], s[22:23], 0, v[148:149]
	global_load_lds_dwordx4 v[246:247], off
	s_mov_b32 m0, s35
	v_lshl_add_u64 v[250:251], s[22:23], 0, v[146:147]
	global_load_lds_dwordx4 v[248:249], off
	s_mov_b32 m0, s36
	s_nop 0
	global_load_lds_dwordx4 v[250:251], off
	s_waitcnt vmcnt(8)
	s_waitcnt lgkmcnt(0)
	s_setprio 1
	s_barrier
	v_mfma_f32_16x16x32_bf16 v[62:65], v[176:179], v[208:211], v[62:65]
	v_mfma_f32_16x16x32_bf16 v[58:61], v[184:187], v[208:211], v[58:61]
	v_mfma_f32_16x16x32_bf16 v[54:57], v[176:179], v[216:219], v[54:57]
	v_mfma_f32_16x16x32_bf16 v[50:53], v[184:187], v[216:219], v[50:53]
	v_mfma_f32_16x16x32_bf16 v[38:41], v[176:179], v[224:227], v[38:41]
	v_mfma_f32_16x16x32_bf16 v[34:37], v[184:187], v[224:227], v[34:37]
	v_mfma_f32_16x16x32_bf16 v[22:25], v[176:179], v[232:235], v[22:25]
	v_mfma_f32_16x16x32_bf16 v[18:21], v[184:187], v[232:235], v[18:21]
	v_mfma_f32_16x16x32_bf16 v[62:65], v[180:183], v[212:215], v[62:65]
	v_mfma_f32_16x16x32_bf16 v[58:61], v[188:191], v[212:215], v[58:61]
	v_mfma_f32_16x16x32_bf16 v[54:57], v[180:183], v[220:223], v[54:57]
	v_mfma_f32_16x16x32_bf16 v[50:53], v[188:191], v[220:223], v[50:53]
	v_mfma_f32_16x16x32_bf16 v[38:41], v[180:183], v[228:231], v[38:41]
	v_mfma_f32_16x16x32_bf16 v[34:37], v[188:191], v[228:231], v[34:37]
	v_mfma_f32_16x16x32_bf16 v[22:25], v[180:183], v[236:239], v[22:25]
	v_mfma_f32_16x16x32_bf16 v[18:21], v[188:191], v[236:239], v[18:21]
	v_mfma_f32_16x16x32_bf16 v[46:49], v[192:195], v[208:211], v[46:49]
	v_mfma_f32_16x16x32_bf16 v[42:45], v[200:203], v[208:211], v[42:45]
	v_mfma_f32_16x16x32_bf16 v[30:33], v[192:195], v[216:219], v[30:33]
	v_mfma_f32_16x16x32_bf16 v[26:29], v[200:203], v[216:219], v[26:29]
	v_mfma_f32_16x16x32_bf16 v[14:17], v[192:195], v[224:227], v[14:17]
	v_mfma_f32_16x16x32_bf16 v[10:13], v[200:203], v[224:227], v[10:13]
	v_mfma_f32_16x16x32_bf16 v[6:9], v[192:195], v[232:235], v[6:9]
	v_mfma_f32_16x16x32_bf16 v[2:5], v[200:203], v[232:235], v[2:5]
	v_mfma_f32_16x16x32_bf16 v[46:49], v[196:199], v[212:215], v[46:49]
	v_mfma_f32_16x16x32_bf16 v[42:45], v[204:207], v[212:215], v[42:45]
	v_mfma_f32_16x16x32_bf16 v[30:33], v[196:199], v[220:223], v[30:33]
	v_mfma_f32_16x16x32_bf16 v[26:29], v[204:207], v[220:223], v[26:29]
	v_mfma_f32_16x16x32_bf16 v[14:17], v[196:199], v[228:231], v[14:17]
	v_mfma_f32_16x16x32_bf16 v[10:13], v[204:207], v[228:231], v[10:13]
	v_mfma_f32_16x16x32_bf16 v[6:9], v[196:199], v[236:239], v[6:9]
	v_mfma_f32_16x16x32_bf16 v[2:5], v[204:207], v[236:239], v[2:5]
	s_barrier
; #define PG8_STAGE(bufoff, gbase, voff) do { _Pragma("unroll") for (int _i = 0; _i < 2; ++_i) \
;         __builtin_amdgcn_global_load_lds((const unsigned*)((const char*)(gbase) + (voff)[_i]), (PG8_LAS unsigned*)(lds + (bufoff) + ldsw + _i * 8192), 16, 0, 0); } while (0)
; #define PG8_LDA(dst, b, h) do { _Pragma("unroll") for (int m = 0; m < 4; ++m) _Pragma("unroll") for (int k = 0; k < 2; ++k) dst[m][k] = *(const PG8_LAS bf16x8*)(lds + PG8_SA(b, h) + aoff + m * 2048 + k * 1024); } while (0)
; #define PG8_LDB(dst, b, h) do { _Pragma("unroll") for (int n = 0; n < 2; ++n) _Pragma("unroll") for (int k = 0; k < 2; ++k) dst[n][k] = *(const PG8_LAS bf16x8*)(lds + PG8_SB(b, h) + boff + n * 2048 + k * 1024); } while (0)
; #define PG8_MMA(ai, bj, At, Bt) do { __builtin_amdgcn_s_setprio(1); _Pragma("unroll") for (int m = 0; m < 4; ++m) _Pragma("unroll") for (int n = 0; n < 2; ++n) _Pragma("unroll") for (int k = 0; k < 2; ++k) \
;         acc[ai][bj][m][n] = __builtin_amdgcn_mfma_f32_16x16x32_bf16(Bt[n][k], At[m][k], acc[ai][bj][m][n], 0, 0, 0); __builtin_amdgcn_s_setprio(0); } while (0)
; #define PG8_WAIT_V(n) asm volatile("s_waitcnt vmcnt(" #n ")" ::: "memory")
; #define PG8_WAIT_L(n) asm volatile("s_waitcnt lgkmcnt(" #n ")" ::: "memory")
; #define PG8_BAR __builtin_amdgcn_s_barrier()
; #define PG8_SCHED __builtin_amdgcn_sched_barrier(0)
; template <class Epi, class Sched, bool ALIGN_EPI = false, bool SP2 = false>
; __device__ __forceinline__ void gemm_phase(PG8_LAS unsigned char* lds, const Gemm g, const Sched& S, const Epi& E) {
;     ...
;             PG8_LDB(B0, 1, 0); PG8_LDB(B1, 1, 1); PG8_SCHED; PG8_LDA(At, 1, 0); PG8_STAGE(PG8_SA(0, 1), a2 + hstep, voffA);
;             PG8_WAIT_V(8); PG8_WAIT_L(0); PG8_BAR; PG8_MMA(0, 0, At, B0); PG8_MMA(0, 1, At, B1); PG8_BAR; PG8_SCHED;
;             PG8_LDA(At, 1, 1); PG8_STAGE(PG8_SB(1, 0), b3, voffB); PG8_STAGE(PG8_SB(1, 1), b3 + hstep, voffB); PG8_STAGE(PG8_SA(1, 0), a3, voffA);
;             PG8_WAIT_V(8); PG8_WAIT_L(0); PG8_BAR; PG8_MMA(1, 0, At, B0); PG8_MMA(1, 1, At, B1); PG8_BAR; PG8_SCHED;
	s_setprio 0
	s_add_i32 s57, 0, 0x18000
	v_add_u32_e32 v175, s57, v172
	s_add_i32 s58, 0, 0x1c000
	ds_read_b128 v[176:179], v175
	ds_read_b128 v[180:183], v175 offset:1024
	ds_read_b128 v[184:187], v175 offset:2048
	ds_read_b128 v[188:191], v175 offset:3072
	v_add_u32_e32 v175, s58, v172
	ds_read_b128 v[192:195], v175
	ds_read_b128 v[196:199], v175 offset:1024
	ds_read_b128 v[200:203], v175 offset:2048
	ds_read_b128 v[204:207], v175 offset:3072
	s_add_u32 s22, s22, s62
	s_addc_u32 s23, s23, 0
	s_mov_b32 m0, s37
	v_lshl_add_u64 v[252:253], s[22:23], 0, v[148:149]
	ds_read_b128 v[208:211], v174 offset:32768
	ds_read_b128 v[212:215], v174 offset:33792
	ds_read_b128 v[216:219], v174 offset:34816
	ds_read_b128 v[220:223], v174 offset:35840
	ds_read_b128 v[224:227], v174 offset:36864
	ds_read_b128 v[228:231], v174 offset:37888
	ds_read_b128 v[232:235], v174 offset:38912
	ds_read_b128 v[236:239], v174 offset:39936
	global_load_lds_dwordx4 v[252:253], off
	v_lshl_add_u64 v[252:253], s[22:23], 0, v[146:147]
	s_mov_b32 m0, s38
	s_nop 0
	global_load_lds_dwordx4 v[252:253], off
	s_waitcnt vmcnt(8)
	s_waitcnt lgkmcnt(0)
	s_setprio 1
	s_barrier
	v_mfma_f32_16x16x32_bf16 v[126:129], v[176:179], v[208:211], v[126:129]
	v_mfma_f32_16x16x32_bf16 v[122:125], v[184:187], v[208:211], v[122:125]
	v_mfma_f32_16x16x32_bf16 v[118:121], v[176:179], v[216:219], v[118:121]
	v_mfma_f32_16x16x32_bf16 v[114:117], v[184:187], v[216:219], v[114:117]
	v_mfma_f32_16x16x32_bf16 v[102:105], v[176:179], v[224:227], v[102:105]
	v_mfma_f32_16x16x32_bf16 v[98:101], v[184:187], v[224:227], v[98:101]
	v_mfma_f32_16x16x32_bf16 v[86:89], v[176:179], v[232:235], v[86:89]
	v_mfma_f32_16x16x32_bf16 v[82:85], v[184:187], v[232:235], v[82:85]
	v_mfma_f32_16x16x32_bf16 v[126:129], v[180:183], v[212:215], v[126:129]
	v_mfma_f32_16x16x32_bf16 v[122:125], v[188:191], v[212:215], v[122:125]
	v_mfma_f32_16x16x32_bf16 v[118:121], v[180:183], v[220:223], v[118:121]
	v_mfma_f32_16x16x32_bf16 v[114:117], v[188:191], v[220:223], v[114:117]
	v_mfma_f32_16x16x32_bf16 v[102:105], v[180:183], v[228:231], v[102:105]
	v_mfma_f32_16x16x32_bf16 v[98:101], v[188:191], v[228:231], v[98:101]
	v_mfma_f32_16x16x32_bf16 v[86:89], v[180:183], v[236:239], v[86:89]
	v_mfma_f32_16x16x32_bf16 v[82:85], v[188:191], v[236:239], v[82:85]
	v_mfma_f32_16x16x32_bf16 v[110:113], v[192:195], v[208:211], v[110:113]
	v_mfma_f32_16x16x32_bf16 v[106:109], v[200:203], v[208:211], v[106:109]
	v_mfma_f32_16x16x32_bf16 v[94:97], v[192:195], v[216:219], v[94:97]
	v_mfma_f32_16x16x32_bf16 v[90:93], v[200:203], v[216:219], v[90:93]
	v_mfma_f32_16x16x32_bf16 v[78:81], v[192:195], v[224:227], v[78:81]
	v_mfma_f32_16x16x32_bf16 v[74:77], v[200:203], v[224:227], v[74:77]
	v_mfma_f32_16x16x32_bf16 v[70:73], v[192:195], v[232:235], v[70:73]
	v_mfma_f32_16x16x32_bf16 v[66:69], v[200:203], v[232:235], v[66:69]
	v_mfma_f32_16x16x32_bf16 v[110:113], v[196:199], v[212:215], v[110:113]
	v_mfma_f32_16x16x32_bf16 v[106:109], v[204:207], v[212:215], v[106:109]
	v_mfma_f32_16x16x32_bf16 v[94:97], v[196:199], v[220:223], v[94:97]
	v_mfma_f32_16x16x32_bf16 v[90:93], v[204:207], v[220:223], v[90:93]
	v_mfma_f32_16x16x32_bf16 v[78:81], v[196:199], v[228:231], v[78:81]
	v_mfma_f32_16x16x32_bf16 v[74:77], v[204:207], v[228:231], v[74:77]
	v_mfma_f32_16x16x32_bf16 v[70:73], v[196:199], v[236:239], v[70:73]
	v_mfma_f32_16x16x32_bf16 v[66:69], v[204:207], v[236:239], v[66:69]
	s_barrier
	s_setprio 0
	s_add_i32 s22, s57, s28
	v_lshl_add_u64 v[240:241], v[240:241], 0, s[86:87]
	s_mov_b32 m0, s22
	ds_read_b128 v[208:211], v174 offset:49152
	ds_read_b128 v[212:215], v174 offset:50176
	ds_read_b128 v[216:219], v174 offset:51200
	ds_read_b128 v[220:223], v174 offset:52224
	ds_read_b128 v[224:227], v174 offset:53248
	ds_read_b128 v[228:231], v174 offset:54272
	ds_read_b128 v[232:235], v174 offset:55296
	ds_read_b128 v[236:239], v174 offset:56320
	global_load_lds_dwordx4 v[240:241], off
	v_lshl_add_u64 v[240:241], v[242:243], 0, s[86:87]
	s_add_i32 m0, s22, 0x2000
	s_add_i32 s22, s58, s28
	global_load_lds_dwordx4 v[240:241], off
	v_lshl_add_u64 v[240:241], v[244:245], 0, s[86:87]
	s_mov_b32 m0, s22
	s_nop 0
	global_load_lds_dwordx4 v[240:241], off
	v_lshl_add_u64 v[240:241], v[246:247], 0, s[86:87]
	s_add_i32 m0, s22, 0x2000
	s_nop 0
	global_load_lds_dwordx4 v[240:241], off
	v_lshl_add_u64 v[240:241], v[248:249], 0, s[86:87]
	s_mov_b32 m0, s40
	s_nop 0
	global_load_lds_dwordx4 v[240:241], off
	v_lshl_add_u64 v[240:241], v[250:251], 0, s[86:87]
	s_mov_b32 m0, s41
	s_nop 0
	global_load_lds_dwordx4 v[240:241], off
	s_waitcnt vmcnt(8)
	s_waitcnt lgkmcnt(0)
	s_setprio 1
	s_barrier
	v_mfma_f32_16x16x32_bf16 v[62:65], v[176:179], v[208:211], v[62:65]
	v_mfma_f32_16x16x32_bf16 v[58:61], v[184:187], v[208:211], v[58:61]
	v_mfma_f32_16x16x32_bf16 v[54:57], v[176:179], v[216:219], v[54:57]
	v_mfma_f32_16x16x32_bf16 v[50:53], v[184:187], v[216:219], v[50:53]
	v_mfma_f32_16x16x32_bf16 v[38:41], v[176:179], v[224:227], v[38:41]
	v_mfma_f32_16x16x32_bf16 v[34:37], v[184:187], v[224:227], v[34:37]
	v_mfma_f32_16x16x32_bf16 v[22:25], v[176:179], v[232:235], v[22:25]
	v_mfma_f32_16x16x32_bf16 v[18:21], v[184:187], v[232:235], v[18:21]
	v_mfma_f32_16x16x32_bf16 v[62:65], v[180:183], v[212:215], v[62:65]
	v_mfma_f32_16x16x32_bf16 v[58:61], v[188:191], v[212:215], v[58:61]
	v_mfma_f32_16x16x32_bf16 v[54:57], v[180:183], v[220:223], v[54:57]
	v_mfma_f32_16x16x32_bf16 v[50:53], v[188:191], v[220:223], v[50:53]
	v_mfma_f32_16x16x32_bf16 v[38:41], v[180:183], v[228:231], v[38:41]
	v_mfma_f32_16x16x32_bf16 v[34:37], v[188:191], v[228:231], v[34:37]
	v_mfma_f32_16x16x32_bf16 v[22:25], v[180:183], v[236:239], v[22:25]
	v_mfma_f32_16x16x32_bf16 v[18:21], v[188:191], v[236:239], v[18:21]
	v_mfma_f32_16x16x32_bf16 v[46:49], v[192:195], v[208:211], v[46:49]
	v_mfma_f32_16x16x32_bf16 v[42:45], v[200:203], v[208:211], v[42:45]
	v_mfma_f32_16x16x32_bf16 v[30:33], v[192:195], v[216:219], v[30:33]
	v_mfma_f32_16x16x32_bf16 v[26:29], v[200:203], v[216:219], v[26:29]
	v_mfma_f32_16x16x32_bf16 v[14:17], v[192:195], v[224:227], v[14:17]
	v_mfma_f32_16x16x32_bf16 v[10:13], v[200:203], v[224:227], v[10:13]
	v_mfma_f32_16x16x32_bf16 v[6:9], v[192:195], v[232:235], v[6:9]
	v_mfma_f32_16x16x32_bf16 v[2:5], v[200:203], v[232:235], v[2:5]
	v_mfma_f32_16x16x32_bf16 v[46:49], v[196:199], v[212:215], v[46:49]
	v_mfma_f32_16x16x32_bf16 v[42:45], v[204:207], v[212:215], v[42:45]
	v_mfma_f32_16x16x32_bf16 v[30:33], v[196:199], v[220:223], v[30:33]
	v_mfma_f32_16x16x32_bf16 v[26:29], v[204:207], v[220:223], v[26:29]
	v_mfma_f32_16x16x32_bf16 v[14:17], v[196:199], v[228:231], v[14:17]
	v_mfma_f32_16x16x32_bf16 v[10:13], v[204:207], v[228:231], v[10:13]
	v_mfma_f32_16x16x32_bf16 v[6:9], v[196:199], v[236:239], v[6:9]
	v_mfma_f32_16x16x32_bf16 v[2:5], v[204:207], v[236:239], v[2:5]
	s_barrier
	s_setprio 0
	s_add_u32 s20, s20, 0x100
	s_addc_u32 s21, s21, 0
	s_add_u32 s54, s54, 0x100
	s_addc_u32 s55, s55, 0
	s_cmp_ge_u32 s56, s39
	s_mov_b32 s22, s56
	s_cbranch_scc0 .LBB0_233

; #define PG8_STAGE(bufoff, gbase, voff) do { _Pragma("unroll") for (int _i = 0; _i < 2; ++_i) \
;         __builtin_amdgcn_global_load_lds((const unsigned*)((const char*)(gbase) + (voff)[_i]), (PG8_LAS unsigned*)(lds + (bufoff) + ldsw + _i * 8192), 16, 0, 0); } while (0)
; #define PG8_LDA(dst, b, h) do { _Pragma("unroll") for (int m = 0; m < 4; ++m) _Pragma("unroll") for (int k = 0; k < 2; ++k) dst[m][k] = *(const PG8_LAS bf16x8*)(lds + PG8_SA(b, h) + aoff + m * 2048 + k * 1024); } while (0)
; #define PG8_LDB(dst, b, h) do { _Pragma("unroll") for (int n = 0; n < 2; ++n) _Pragma("unroll") for (int k = 0; k < 2; ++k) dst[n][k] = *(const PG8_LAS bf16x8*)(lds + PG8_SB(b, h) + boff + n * 2048 + k * 1024); } while (0)
; #define PG8_WAIT_V(n) asm volatile("s_waitcnt vmcnt(" #n ")" ::: "memory")
; #define PG8_WAIT_L(n) asm volatile("s_waitcnt lgkmcnt(" #n ")" ::: "memory")
; #define PG8_BAR __builtin_amdgcn_s_barrier()
; #define PG8_SCHED __builtin_amdgcn_sched_barrier(0)
; template <class Epi, class Sched, bool ALIGN_EPI = false, bool SP2 = false>
; __device__ __forceinline__ void gemm_phase(PG8_LAS unsigned char* lds, const Gemm g, const Sched& S, const Epi& E) {
;     ...
;         const bool has_next = S.next(ui + 1, nxt);
;         const char* nA = has_next ? (const char*)g.A + (size_t)nxt.pm * tstep : cA; const char* nB = has_next ? (const char*)g.Bt + (size_t)nxt.pn * tstep : cB;
;         for (int t = 0; t < nt; t += 2) {
;             const bool last = (t == nt - 2);
;             const char* a1 = cA + (size_t)(t + 1) * kstep;
;             const char* a2 = last ? nA : cA + (size_t)(t + 2) * kstep; const char* b2 = last ? nB : cB + (size_t)(t + 2) * kstep;
;             const char* a3 = a2 + kstep; const char* b3 = b2 + kstep;
;             if (last && has_next) S.a_ready(nxt);
;             if constexpr (SP2) {
;             PG8_LDB(B0, 0, 0); PG8_LDB(B1, 0, 1); PG8_SCHED; PG8_LDA(At, 0, 0); PG8_STAGE(PG8_SA(1, 1), a1 + hstep, voffA);
;             PG8_WAIT_V(8); PG8_WAIT_L(0); PG8_BAR; PG8_MMA(0, 0, At, B0); PG8_MMA(0, 1, At, B1); PG8_BAR; PG8_SCHED;
;             PG8_LDA(At, 0, 1); PG8_STAGE(PG8_SB(0, 0), b2, voffB); PG8_STAGE(PG8_SB(0, 1), b2 + hstep, voffB); PG8_STAGE(PG8_SA(0, 0), a2, voffA);
;             PG8_WAIT_V(8); PG8_WAIT_L(0); PG8_BAR; PG8_MMA(1, 0, At, B0); PG8_MMA(1, 1, At, B1); PG8_BAR; PG8_SCHED;
.LBB0_283:
	s_ashr_i32 s15, s14, 31
	s_lshl_b64 s[16:17], s[14:15], 19
	s_add_u32 s16, s92, s16
	s_addc_u32 s17, s93, s17
	s_and_b64 s[18:19], s[6:7], exec
	s_cselect_b32 s15, s17, s21
	s_cselect_b32 s38, s16, s20
	s_ashr_i32 s13, s12, 31
	s_lshl_b64 s[18:19], s[12:13], 19
	s_add_u32 s18, s1, s18
	s_addc_u32 s19, s5, s19
	s_and_b64 s[24:25], s[6:7], exec
	s_cselect_b32 s13, s19, s23
	s_cselect_b32 s39, s18, s22
	s_add_u32 s20, s20, 0x40080
	s_addc_u32 s21, s21, 0
	s_add_u32 s40, s22, 0x100
	s_addc_u32 s41, s23, 0
	s_mov_b32 s42, -2
	s_add_u32 s22, s20, 0xfffc0080
	s_addc_u32 s23, s21, -1
	s_add_i32 s43, 0, 0x10000
	s_cmp_eq_u32 s42, 12
	s_cselect_b32 s25, s15, s23
	s_cselect_b32 s24, s38, s22
	v_add_u32_e32 v144, s43, v146
	s_cselect_b32 s23, s13, s41
	s_cselect_b32 s22, s39, s40
	s_add_i32 s46, 0, 0x14000
	ds_read_b128 v[150:153], v144
	ds_read_b128 v[172:175], v144 offset:1024
	ds_read_b128 v[176:179], v144 offset:2048
	ds_read_b128 v[180:183], v144 offset:3072
	v_add_u32_e32 v144, s46, v146
	ds_read_b128 v[184:187], v144
	ds_read_b128 v[188:191], v144 offset:1024
	ds_read_b128 v[192:195], v144 offset:2048
	ds_read_b128 v[196:199], v144 offset:3072
	v_lshl_add_u64 v[144:145], s[20:21], 0, v[138:139]
	s_add_i32 m0, s27, 0xc000
	ds_read_b128 v[200:203], v148
	ds_read_b128 v[204:207], v148 offset:1024
	ds_read_b128 v[208:211], v148 offset:2048
	ds_read_b128 v[212:215], v148 offset:3072
	ds_read_b128 v[216:219], v148 offset:4096
	ds_read_b128 v[220:223], v148 offset:5120
	ds_read_b128 v[224:227], v148 offset:6144
	ds_read_b128 v[228:231], v148 offset:7168
	global_load_lds_dwordx4 v[144:145], off
	v_lshl_add_u64 v[144:145], s[20:21], 0, v[140:141]
	s_add_i32 m0, s27, 0xe000
	s_nop 0
	global_load_lds_dwordx4 v[144:145], off
	s_waitcnt vmcnt(8)
	s_waitcnt lgkmcnt(0)
	s_setprio 1
	s_barrier
	v_mfma_f32_16x16x32_bf16 v[126:129], v[150:153], v[200:203], 0
	v_mfma_f32_16x16x32_bf16 v[122:125], v[176:179], v[200:203], 0
	v_mfma_f32_16x16x32_bf16 v[110:113], v[150:153], v[208:211], 0
	v_mfma_f32_16x16x32_bf16 v[106:109], v[176:179], v[208:211], 0
	v_mfma_f32_16x16x32_bf16 v[94:97], v[150:153], v[216:219], 0
	v_mfma_f32_16x16x32_bf16 v[90:93], v[176:179], v[216:219], 0
	v_mfma_f32_16x16x32_bf16 v[78:81], v[150:153], v[224:227], 0
	v_mfma_f32_16x16x32_bf16 v[74:77], v[176:179], v[224:227], 0
	v_mfma_f32_16x16x32_bf16 v[126:129], v[172:175], v[204:207], v[126:129]
	v_mfma_f32_16x16x32_bf16 v[122:125], v[180:183], v[204:207], v[122:125]
	v_mfma_f32_16x16x32_bf16 v[110:113], v[172:175], v[212:215], v[110:113]
	v_mfma_f32_16x16x32_bf16 v[106:109], v[180:183], v[212:215], v[106:109]
	v_mfma_f32_16x16x32_bf16 v[94:97], v[172:175], v[220:223], v[94:97]
	v_mfma_f32_16x16x32_bf16 v[90:93], v[180:183], v[220:223], v[90:93]
	v_mfma_f32_16x16x32_bf16 v[78:81], v[172:175], v[228:231], v[78:81]
	v_mfma_f32_16x16x32_bf16 v[74:77], v[180:183], v[228:231], v[74:77]
	v_mfma_f32_16x16x32_bf16 v[118:121], v[184:187], v[200:203], 0
	v_mfma_f32_16x16x32_bf16 v[114:117], v[192:195], v[200:203], 0
	v_mfma_f32_16x16x32_bf16 v[102:105], v[184:187], v[208:211], 0
	v_mfma_f32_16x16x32_bf16 v[98:101], v[192:195], v[208:211], 0
	v_mfma_f32_16x16x32_bf16 v[86:89], v[184:187], v[216:219], 0
	v_mfma_f32_16x16x32_bf16 v[82:85], v[192:195], v[216:219], 0
	v_mfma_f32_16x16x32_bf16 v[70:73], v[184:187], v[224:227], 0
	v_mfma_f32_16x16x32_bf16 v[66:69], v[192:195], v[224:227], 0
	v_mfma_f32_16x16x32_bf16 v[118:121], v[188:191], v[204:207], v[118:121]
	v_mfma_f32_16x16x32_bf16 v[114:117], v[196:199], v[204:207], v[114:117]
	v_mfma_f32_16x16x32_bf16 v[102:105], v[188:191], v[212:215], v[102:105]
	v_mfma_f32_16x16x32_bf16 v[98:101], v[196:199], v[212:215], v[98:101]
	v_mfma_f32_16x16x32_bf16 v[86:89], v[188:191], v[220:223], v[86:89]
	v_mfma_f32_16x16x32_bf16 v[82:85], v[196:199], v[220:223], v[82:85]
	v_mfma_f32_16x16x32_bf16 v[70:73], v[188:191], v[228:231], v[70:73]
	v_mfma_f32_16x16x32_bf16 v[66:69], v[196:199], v[228:231], v[66:69]
	s_barrier
	s_setprio 0
	s_add_i32 s43, s43, s26
	v_lshl_add_u64 v[144:145], s[22:23], 0, v[134:135]
	s_mov_b32 m0, s43
	ds_read_b128 v[200:203], v148 offset:16384
	ds_read_b128 v[204:207], v148 offset:17408
	ds_read_b128 v[208:211], v148 offset:18432
	ds_read_b128 v[212:215], v148 offset:19456
	ds_read_b128 v[216:219], v148 offset:20480
	ds_read_b128 v[220:223], v148 offset:21504
	ds_read_b128 v[224:227], v148 offset:22528
	ds_read_b128 v[228:231], v148 offset:23552
	global_load_lds_dwordx4 v[144:145], off
	s_add_i32 m0, s43, 0x2000
	s_add_u32 s44, s22, 0x40000
	v_lshl_add_u64 v[232:233], s[22:23], 0, v[130:131]
	s_addc_u32 s45, s23, 0
	s_add_i32 s43, s46, s26
	global_load_lds_dwordx4 v[232:233], off
	v_lshl_add_u64 v[234:235], s[44:45], 0, v[134:135]
	s_mov_b32 m0, s43
	v_lshl_add_u64 v[236:237], s[24:25], 0, v[132:133]
	global_load_lds_dwordx4 v[234:235], off
	v_lshl_add_u64 v[234:235], s[44:45], 0, v[130:131]
	s_add_i32 m0, s43, 0x2000
	s_nop 0
	global_load_lds_dwordx4 v[234:235], off
	v_lshl_add_u64 v[234:235], s[24:25], 0, v[136:137]
	s_mov_b32 m0, s27
	s_nop 0
	global_load_lds_dwordx4 v[234:235], off
	s_mov_b32 m0, s28
	s_nop 0
	global_load_lds_dwordx4 v[236:237], off
	s_waitcnt vmcnt(8)
	s_waitcnt lgkmcnt(0)
	s_setprio 1
	s_barrier
; #define PG8_STAGE(bufoff, gbase, voff) do { _Pragma("unroll") for (int _i = 0; _i < 2; ++_i) \
;         __builtin_amdgcn_global_load_lds((const unsigned*)((const char*)(gbase) + (voff)[_i]), (PG8_LAS unsigned*)(lds + (bufoff) + ldsw + _i * 8192), 16, 0, 0); } while (0)
; #define PG8_LDA(dst, b, h) do { _Pragma("unroll") for (int m = 0; m < 4; ++m) _Pragma("unroll") for (int k = 0; k < 2; ++k) dst[m][k] = *(const PG8_LAS bf16x8*)(lds + PG8_SA(b, h) + aoff + m * 2048 + k * 1024); } while (0)
; #define PG8_LDB(dst, b, h) do { _Pragma("unroll") for (int n = 0; n < 2; ++n) _Pragma("unroll") for (int k = 0; k < 2; ++k) dst[n][k] = *(const PG8_LAS bf16x8*)(lds + PG8_SB(b, h) + boff + n * 2048 + k * 1024); } while (0)
; #define PG8_MMA(ai, bj, At, Bt) do { __builtin_amdgcn_s_setprio(1); _Pragma("unroll") for (int m = 0; m < 4; ++m) _Pragma("unroll") for (int n = 0; n < 2; ++n) _Pragma("unroll") for (int k = 0; k < 2; ++k) \
;         acc[ai][bj][m][n] = __builtin_amdgcn_mfma_f32_16x16x32_bf16(Bt[n][k], At[m][k], acc[ai][bj][m][n], 0, 0, 0); __builtin_amdgcn_s_setprio(0); } while (0)
; #define PG8_WAIT_V(n) asm volatile("s_waitcnt vmcnt(" #n ")" ::: "memory")
; #define PG8_WAIT_L(n) asm volatile("s_waitcnt lgkmcnt(" #n ")" ::: "memory")
; #define PG8_BAR __builtin_amdgcn_s_barrier()
; #define PG8_SCHED __builtin_amdgcn_sched_barrier(0)
; template <class Epi, class Sched, bool ALIGN_EPI = false, bool SP2 = false>
; __device__ __forceinline__ void gemm_phase(PG8_LAS unsigned char* lds, const Gemm g, const Sched& S, const Epi& E) {
;     ...
;             PG8_WAIT_V(8); PG8_WAIT_L(0); PG8_BAR; PG8_MMA(1, 0, At, B0); PG8_MMA(1, 1, At, B1); PG8_BAR; PG8_SCHED;
;             PG8_LDB(B0, 1, 0); PG8_LDB(B1, 1, 1); PG8_SCHED; PG8_LDA(At, 1, 0); PG8_STAGE(PG8_SA(0, 1), a2 + hstep, voffA);
;             PG8_WAIT_V(8); PG8_WAIT_L(0); PG8_BAR; PG8_MMA(0, 0, At, B0); PG8_MMA(0, 1, At, B1); PG8_BAR; PG8_SCHED;
	v_mfma_f32_16x16x32_bf16 v[62:65], v[150:153], v[200:203], 0
	v_mfma_f32_16x16x32_bf16 v[58:61], v[176:179], v[200:203], 0
	v_mfma_f32_16x16x32_bf16 v[46:49], v[150:153], v[208:211], 0
	v_mfma_f32_16x16x32_bf16 v[42:45], v[176:179], v[208:211], 0
	v_mfma_f32_16x16x32_bf16 v[30:33], v[150:153], v[216:219], 0
	v_mfma_f32_16x16x32_bf16 v[26:29], v[176:179], v[216:219], 0
	v_mfma_f32_16x16x32_bf16 v[14:17], v[150:153], v[224:227], 0
	v_mfma_f32_16x16x32_bf16 v[10:13], v[176:179], v[224:227], 0
	v_mfma_f32_16x16x32_bf16 v[62:65], v[172:175], v[204:207], v[62:65]
	v_mfma_f32_16x16x32_bf16 v[58:61], v[180:183], v[204:207], v[58:61]
	v_mfma_f32_16x16x32_bf16 v[46:49], v[172:175], v[212:215], v[46:49]
	v_mfma_f32_16x16x32_bf16 v[42:45], v[180:183], v[212:215], v[42:45]
	v_mfma_f32_16x16x32_bf16 v[30:33], v[172:175], v[220:223], v[30:33]
	v_mfma_f32_16x16x32_bf16 v[26:29], v[180:183], v[220:223], v[26:29]
	v_mfma_f32_16x16x32_bf16 v[14:17], v[172:175], v[228:231], v[14:17]
	v_mfma_f32_16x16x32_bf16 v[10:13], v[180:183], v[228:231], v[10:13]
	v_mfma_f32_16x16x32_bf16 v[54:57], v[184:187], v[200:203], 0
	v_mfma_f32_16x16x32_bf16 v[50:53], v[192:195], v[200:203], 0
	v_mfma_f32_16x16x32_bf16 v[38:41], v[184:187], v[208:211], 0
	v_mfma_f32_16x16x32_bf16 v[34:37], v[192:195], v[208:211], 0
	v_mfma_f32_16x16x32_bf16 v[22:25], v[184:187], v[216:219], 0
	v_mfma_f32_16x16x32_bf16 v[18:21], v[192:195], v[216:219], 0
	v_mfma_f32_16x16x32_bf16 v[6:9], v[184:187], v[224:227], 0
	v_mfma_f32_16x16x32_bf16 v[2:5], v[192:195], v[224:227], 0
	v_mfma_f32_16x16x32_bf16 v[54:57], v[188:191], v[204:207], v[54:57]
	v_mfma_f32_16x16x32_bf16 v[50:53], v[196:199], v[204:207], v[50:53]
	v_mfma_f32_16x16x32_bf16 v[38:41], v[188:191], v[212:215], v[38:41]
	v_mfma_f32_16x16x32_bf16 v[34:37], v[196:199], v[212:215], v[34:37]
	v_mfma_f32_16x16x32_bf16 v[22:25], v[188:191], v[220:223], v[22:25]
	v_mfma_f32_16x16x32_bf16 v[18:21], v[196:199], v[220:223], v[18:21]
	v_mfma_f32_16x16x32_bf16 v[6:9], v[188:191], v[228:231], v[6:9]
	v_mfma_f32_16x16x32_bf16 v[2:5], v[196:199], v[228:231], v[2:5]
	s_barrier
	s_setprio 0
	s_add_i32 s43, 0, 0x18000
	v_add_u32_e32 v149, s43, v146
	s_add_i32 s44, 0, 0x1c000
	ds_read_b128 v[150:153], v149
	ds_read_b128 v[172:175], v149 offset:1024
	ds_read_b128 v[176:179], v149 offset:2048
	ds_read_b128 v[180:183], v149 offset:3072
	v_add_u32_e32 v149, s44, v146
	ds_read_b128 v[184:187], v149
	ds_read_b128 v[188:191], v149 offset:1024
	ds_read_b128 v[192:195], v149 offset:2048
	ds_read_b128 v[196:199], v149 offset:3072
	s_add_u32 s24, s24, 0x40000
	s_addc_u32 s25, s25, 0
	s_mov_b32 m0, s29
	v_lshl_add_u64 v[238:239], s[24:25], 0, v[136:137]
	ds_read_b128 v[200:203], v148 offset:32768
	ds_read_b128 v[204:207], v148 offset:33792
	ds_read_b128 v[208:211], v148 offset:34816
	ds_read_b128 v[212:215], v148 offset:35840
	ds_read_b128 v[216:219], v148 offset:36864
	ds_read_b128 v[220:223], v148 offset:37888
	ds_read_b128 v[224:227], v148 offset:38912
	ds_read_b128 v[228:231], v148 offset:39936
	global_load_lds_dwordx4 v[238:239], off
	v_lshl_add_u64 v[238:239], s[24:25], 0, v[132:133]
	s_mov_b32 m0, s30
	s_nop 0
	global_load_lds_dwordx4 v[238:239], off
	s_waitcnt vmcnt(8)
	s_waitcnt lgkmcnt(0)
	s_setprio 1
	s_barrier
	v_mfma_f32_16x16x32_bf16 v[126:129], v[150:153], v[200:203], v[126:129]
	v_mfma_f32_16x16x32_bf16 v[122:125], v[176:179], v[200:203], v[122:125]
	v_mfma_f32_16x16x32_bf16 v[110:113], v[150:153], v[208:211], v[110:113]
	v_mfma_f32_16x16x32_bf16 v[106:109], v[176:179], v[208:211], v[106:109]
	v_mfma_f32_16x16x32_bf16 v[94:97], v[150:153], v[216:219], v[94:97]
	v_mfma_f32_16x16x32_bf16 v[90:93], v[176:179], v[216:219], v[90:93]
	v_mfma_f32_16x16x32_bf16 v[78:81], v[150:153], v[224:227], v[78:81]
	v_mfma_f32_16x16x32_bf16 v[74:77], v[176:179], v[224:227], v[74:77]
	v_mfma_f32_16x16x32_bf16 v[126:129], v[172:175], v[204:207], v[126:129]
	v_mfma_f32_16x16x32_bf16 v[122:125], v[180:183], v[204:207], v[122:125]
	v_mfma_f32_16x16x32_bf16 v[110:113], v[172:175], v[212:215], v[110:113]
	v_mfma_f32_16x16x32_bf16 v[106:109], v[180:183], v[212:215], v[106:109]
	v_mfma_f32_16x16x32_bf16 v[94:97], v[172:175], v[220:223], v[94:97]
	v_mfma_f32_16x16x32_bf16 v[90:93], v[180:183], v[220:223], v[90:93]
	v_mfma_f32_16x16x32_bf16 v[78:81], v[172:175], v[228:231], v[78:81]
	v_mfma_f32_16x16x32_bf16 v[74:77], v[180:183], v[228:231], v[74:77]
	v_mfma_f32_16x16x32_bf16 v[118:121], v[184:187], v[200:203], v[118:121]
	v_mfma_f32_16x16x32_bf16 v[114:117], v[192:195], v[200:203], v[114:117]
	v_mfma_f32_16x16x32_bf16 v[102:105], v[184:187], v[208:211], v[102:105]
	v_mfma_f32_16x16x32_bf16 v[98:101], v[192:195], v[208:211], v[98:101]
	v_mfma_f32_16x16x32_bf16 v[86:89], v[184:187], v[216:219], v[86:89]
	v_mfma_f32_16x16x32_bf16 v[82:85], v[192:195], v[216:219], v[82:85]
	v_mfma_f32_16x16x32_bf16 v[70:73], v[184:187], v[224:227], v[70:73]
	v_mfma_f32_16x16x32_bf16 v[66:69], v[192:195], v[224:227], v[66:69]
	v_mfma_f32_16x16x32_bf16 v[118:121], v[188:191], v[204:207], v[118:121]
	v_mfma_f32_16x16x32_bf16 v[114:117], v[196:199], v[204:207], v[114:117]
	v_mfma_f32_16x16x32_bf16 v[102:105], v[188:191], v[212:215], v[102:105]
	v_mfma_f32_16x16x32_bf16 v[98:101], v[196:199], v[212:215], v[98:101]
	v_mfma_f32_16x16x32_bf16 v[86:89], v[188:191], v[220:223], v[86:89]
	v_mfma_f32_16x16x32_bf16 v[82:85], v[196:199], v[220:223], v[82:85]
	v_mfma_f32_16x16x32_bf16 v[70:73], v[188:191], v[228:231], v[70:73]
	v_mfma_f32_16x16x32_bf16 v[66:69], v[196:199], v[228:231], v[66:69]
	s_barrier
; #define PG8_STAGE(bufoff, gbase, voff) do { _Pragma("unroll") for (int _i = 0; _i < 2; ++_i) \
;         __builtin_amdgcn_global_load_lds((const unsigned*)((const char*)(gbase) + (voff)[_i]), (PG8_LAS unsigned*)(lds + (bufoff) + ldsw + _i * 8192), 16, 0, 0); } while (0)
; #define PG8_LDA(dst, b, h) do { _Pragma("unroll") for (int m = 0; m < 4; ++m) _Pragma("unroll") for (int k = 0; k < 2; ++k) dst[m][k] = *(const PG8_LAS bf16x8*)(lds + PG8_SA(b, h) + aoff + m * 2048 + k * 1024); } while (0)
; #define PG8_LDB(dst, b, h) do { _Pragma("unroll") for (int n = 0; n < 2; ++n) _Pragma("unroll") for (int k = 0; k < 2; ++k) dst[n][k] = *(const PG8_LAS bf16x8*)(lds + PG8_SB(b, h) + boff + n * 2048 + k * 1024); } while (0)
; template <class Epi, class Sched, bool ALIGN_EPI = false, bool SP2 = false>
; __device__ __forceinline__ void gemm_phase(PG8_LAS unsigned char* lds, const Gemm g, const Sched& S, const Epi& E) {
;     ...
;         for (int t = 0; t < nt; t += 2) {
;             const bool last = (t == nt - 2);
;             const char* a1 = cA + (size_t)(t + 1) * kstep;
;             const char* a2 = last ? nA : cA + (size_t)(t + 2) * kstep; const char* b2 = last ? nB : cB + (size_t)(t + 2) * kstep;
;             const char* a3 = a2 + kstep; const char* b3 = b2 + kstep;
;             if (last && has_next) S.a_ready(nxt);
;             if constexpr (SP2) {
;             PG8_LDB(B0, 0, 0); PG8_LDB(B1, 0, 1); PG8_SCHED; PG8_LDA(At, 0, 0); PG8_STAGE(PG8_SA(1, 1), a1 + hstep, voffA);
;             PG8_WAIT_V(8); PG8_WAIT_L(0); PG8_BAR; PG8_MMA(0, 0, At, B0); PG8_MMA(0, 1, At, B1); PG8_BAR; PG8_SCHED;
;             PG8_LDA(At, 0, 1); PG8_STAGE(PG8_SB(0, 0), b2, voffB); PG8_STAGE(PG8_SB(0, 1), b2 + hstep, voffB); PG8_STAGE(PG8_SA(0, 0), a2, voffA);
;             PG8_WAIT_V(8); PG8_WAIT_L(0); PG8_BAR; PG8_MMA(1, 0, At, B0); PG8_MMA(1, 1, At, B1); PG8_BAR; PG8_SCHED;
;             PG8_LDB(B0, 1, 0); PG8_LDB(B1, 1, 1); PG8_SCHED; PG8_LDA(At, 1, 0); PG8_STAGE(PG8_SA(0, 1), a2 + hstep, voffA);
;             PG8_WAIT_V(8); PG8_WAIT_L(0); PG8_BAR; PG8_MMA(0, 0, At, B0); PG8_MMA(0, 1, At, B1); PG8_BAR; PG8_SCHED;
;             PG8_LDA(At, 1, 1); PG8_STAGE(PG8_SB(1, 0), b3, voffB); PG8_STAGE(PG8_SB(1, 1), b3 + hstep, voffB); PG8_STAGE(PG8_SA(1, 0), a3, voffA);
;             PG8_WAIT_V(8); PG8_WAIT_L(0); PG8_BAR; PG8_MMA(1, 0, At, B0); PG8_MMA(1, 1, At, B1); PG8_BAR; PG8_SCHED;
	s_setprio 0
	s_add_i32 s24, s43, s26
	v_lshl_add_u64 v[144:145], v[144:145], 0, s[86:87]
	s_mov_b32 m0, s24
	ds_read_b128 v[200:203], v148 offset:49152
	ds_read_b128 v[204:207], v148 offset:50176
	ds_read_b128 v[208:211], v148 offset:51200
	ds_read_b128 v[212:215], v148 offset:52224
	ds_read_b128 v[216:219], v148 offset:53248
	ds_read_b128 v[220:223], v148 offset:54272
	ds_read_b128 v[224:227], v148 offset:55296
	ds_read_b128 v[228:231], v148 offset:56320
	global_load_lds_dwordx4 v[144:145], off
	s_add_i32 m0, s24, 0x2000
	s_add_u32 s22, s22, 0x40080
	v_lshl_add_u64 v[144:145], v[232:233], 0, s[86:87]
	s_addc_u32 s23, s23, 0
	s_add_i32 s24, s44, s26
	global_load_lds_dwordx4 v[144:145], off
	v_lshl_add_u64 v[144:145], s[22:23], 0, v[134:135]
	s_mov_b32 m0, s24
	s_nop 0
	global_load_lds_dwordx4 v[144:145], off
	v_lshl_add_u64 v[144:145], s[22:23], 0, v[130:131]
	s_add_i32 m0, s24, 0x2000
	s_nop 0
	global_load_lds_dwordx4 v[144:145], off
	v_lshl_add_u64 v[144:145], v[234:235], 0, s[86:87]
	s_mov_b32 m0, s31
	s_nop 0
	global_load_lds_dwordx4 v[144:145], off
	v_lshl_add_u64 v[144:145], v[236:237], 0, s[86:87]
	s_mov_b32 m0, s34
	s_nop 0
	global_load_lds_dwordx4 v[144:145], off
	s_waitcnt vmcnt(8)
	s_waitcnt lgkmcnt(0)
	s_setprio 1
	s_barrier
	v_mfma_f32_16x16x32_bf16 v[62:65], v[150:153], v[200:203], v[62:65]
	v_mfma_f32_16x16x32_bf16 v[58:61], v[176:179], v[200:203], v[58:61]
	v_mfma_f32_16x16x32_bf16 v[46:49], v[150:153], v[208:211], v[46:49]
	v_mfma_f32_16x16x32_bf16 v[42:45], v[176:179], v[208:211], v[42:45]
	v_mfma_f32_16x16x32_bf16 v[30:33], v[150:153], v[216:219], v[30:33]
	v_mfma_f32_16x16x32_bf16 v[26:29], v[176:179], v[216:219], v[26:29]
	v_mfma_f32_16x16x32_bf16 v[14:17], v[150:153], v[224:227], v[14:17]
	v_mfma_f32_16x16x32_bf16 v[10:13], v[176:179], v[224:227], v[10:13]
	v_mfma_f32_16x16x32_bf16 v[62:65], v[172:175], v[204:207], v[62:65]
	v_mfma_f32_16x16x32_bf16 v[58:61], v[180:183], v[204:207], v[58:61]
	v_mfma_f32_16x16x32_bf16 v[46:49], v[172:175], v[212:215], v[46:49]
	v_mfma_f32_16x16x32_bf16 v[42:45], v[180:183], v[212:215], v[42:45]
	v_mfma_f32_16x16x32_bf16 v[30:33], v[172:175], v[220:223], v[30:33]
	v_mfma_f32_16x16x32_bf16 v[26:29], v[180:183], v[220:223], v[26:29]
	v_mfma_f32_16x16x32_bf16 v[14:17], v[172:175], v[228:231], v[14:17]
	v_mfma_f32_16x16x32_bf16 v[10:13], v[180:183], v[228:231], v[10:13]
	v_mfma_f32_16x16x32_bf16 v[54:57], v[184:187], v[200:203], v[54:57]
	v_mfma_f32_16x16x32_bf16 v[50:53], v[192:195], v[200:203], v[50:53]
	v_mfma_f32_16x16x32_bf16 v[38:41], v[184:187], v[208:211], v[38:41]
	v_mfma_f32_16x16x32_bf16 v[34:37], v[192:195], v[208:211], v[34:37]
	v_mfma_f32_16x16x32_bf16 v[22:25], v[184:187], v[216:219], v[22:25]
	v_mfma_f32_16x16x32_bf16 v[18:21], v[192:195], v[216:219], v[18:21]
	v_mfma_f32_16x16x32_bf16 v[6:9], v[184:187], v[224:227], v[6:9]
	v_mfma_f32_16x16x32_bf16 v[2:5], v[192:195], v[224:227], v[2:5]
	v_mfma_f32_16x16x32_bf16 v[54:57], v[188:191], v[204:207], v[54:57]
	v_mfma_f32_16x16x32_bf16 v[50:53], v[196:199], v[204:207], v[50:53]
	v_mfma_f32_16x16x32_bf16 v[38:41], v[188:191], v[212:215], v[38:41]
	v_mfma_f32_16x16x32_bf16 v[34:37], v[196:199], v[212:215], v[34:37]
	v_mfma_f32_16x16x32_bf16 v[22:25], v[188:191], v[220:223], v[22:25]
	v_mfma_f32_16x16x32_bf16 v[18:21], v[196:199], v[220:223], v[18:21]
	v_mfma_f32_16x16x32_bf16 v[6:9], v[188:191], v[228:231], v[6:9]
	v_mfma_f32_16x16x32_bf16 v[2:5], v[196:199], v[228:231], v[2:5]
	s_barrier
	s_setprio 0
	s_add_i32 s42, s42, 2
	s_add_u32 s20, s20, 0x100
	s_addc_u32 s21, s21, 0
	s_add_u32 s40, s40, 0x100
	s_addc_u32 s41, s41, 0
	s_cmp_gt_u32 s42, 13
	s_cbranch_scc1 .Lpeel_after_B
.LBB0_284:
	s_add_u32 s22, s20, 0xfffc0080
	s_addc_u32 s23, s21, -1
	s_add_i32 s43, 0, 0x10000
	s_cmp_eq_u32 s42, 12
	s_cselect_b32 s25, s15, s23
	s_cselect_b32 s24, s38, s22
	v_add_u32_e32 v144, s43, v146
	s_cselect_b32 s23, s13, s41
	s_cselect_b32 s22, s39, s40
	s_add_i32 s46, 0, 0x14000
	ds_read_b128 v[150:153], v144
	ds_read_b128 v[172:175], v144 offset:1024
	ds_read_b128 v[176:179], v144 offset:2048
	ds_read_b128 v[180:183], v144 offset:3072
	v_add_u32_e32 v144, s46, v146
	ds_read_b128 v[184:187], v144
	ds_read_b128 v[188:191], v144 offset:1024
	ds_read_b128 v[192:195], v144 offset:2048
	ds_read_b128 v[196:199], v144 offset:3072
	v_lshl_add_u64 v[144:145], s[20:21], 0, v[138:139]
	s_add_i32 m0, s27, 0xc000
	ds_read_b128 v[200:203], v148
	ds_read_b128 v[204:207], v148 offset:1024
	ds_read_b128 v[208:211], v148 offset:2048
	ds_read_b128 v[212:215], v148 offset:3072
	ds_read_b128 v[216:219], v148 offset:4096
	ds_read_b128 v[220:223], v148 offset:5120
	ds_read_b128 v[224:227], v148 offset:6144
	ds_read_b128 v[228:231], v148 offset:7168
	global_load_lds_dwordx4 v[144:145], off
	v_lshl_add_u64 v[144:145], s[20:21], 0, v[140:141]
	s_add_i32 m0, s27, 0xe000
	s_nop 0
	global_load_lds_dwordx4 v[144:145], off
	s_waitcnt vmcnt(8)
	s_waitcnt lgkmcnt(0)
	s_setprio 1
	s_barrier
; #define PG8_STAGE(bufoff, gbase, voff) do { _Pragma("unroll") for (int _i = 0; _i < 2; ++_i) \
;         __builtin_amdgcn_global_load_lds((const unsigned*)((const char*)(gbase) + (voff)[_i]), (PG8_LAS unsigned*)(lds + (bufoff) + ldsw + _i * 8192), 16, 0, 0); } while (0)
; #define PG8_LDA(dst, b, h) do { _Pragma("unroll") for (int m = 0; m < 4; ++m) _Pragma("unroll") for (int k = 0; k < 2; ++k) dst[m][k] = *(const PG8_LAS bf16x8*)(lds + PG8_SA(b, h) + aoff + m * 2048 + k * 1024); } while (0)
; #define PG8_LDB(dst, b, h) do { _Pragma("unroll") for (int n = 0; n < 2; ++n) _Pragma("unroll") for (int k = 0; k < 2; ++k) dst[n][k] = *(const PG8_LAS bf16x8*)(lds + PG8_SB(b, h) + boff + n * 2048 + k * 1024); } while (0)
; #define PG8_MMA(ai, bj, At, Bt) do { __builtin_amdgcn_s_setprio(1); _Pragma("unroll") for (int m = 0; m < 4; ++m) _Pragma("unroll") for (int n = 0; n < 2; ++n) _Pragma("unroll") for (int k = 0; k < 2; ++k) \
;         acc[ai][bj][m][n] = __builtin_amdgcn_mfma_f32_16x16x32_bf16(Bt[n][k], At[m][k], acc[ai][bj][m][n], 0, 0, 0); __builtin_amdgcn_s_setprio(0); } while (0)
; #define PG8_WAIT_V(n) asm volatile("s_waitcnt vmcnt(" #n ")" ::: "memory")
; #define PG8_WAIT_L(n) asm volatile("s_waitcnt lgkmcnt(" #n ")" ::: "memory")
; #define PG8_BAR __builtin_amdgcn_s_barrier()
; #define PG8_SCHED __builtin_amdgcn_sched_barrier(0)
; template <class Epi, class Sched, bool ALIGN_EPI = false, bool SP2 = false>
; __device__ __forceinline__ void gemm_phase(PG8_LAS unsigned char* lds, const Gemm g, const Sched& S, const Epi& E) {
;     ...
;             PG8_LDB(B0, 0, 0); PG8_LDB(B1, 0, 1); PG8_SCHED; PG8_LDA(At, 0, 0); PG8_STAGE(PG8_SA(1, 1), a1 + hstep, voffA);
;             PG8_WAIT_V(8); PG8_WAIT_L(0); PG8_BAR; PG8_MMA(0, 0, At, B0); PG8_MMA(0, 1, At, B1); PG8_BAR; PG8_SCHED;
;             PG8_LDA(At, 0, 1); PG8_STAGE(PG8_SB(0, 0), b2, voffB); PG8_STAGE(PG8_SB(0, 1), b2 + hstep, voffB); PG8_STAGE(PG8_SA(0, 0), a2, voffA);
;             PG8_WAIT_V(8); PG8_WAIT_L(0); PG8_BAR; PG8_MMA(1, 0, At, B0); PG8_MMA(1, 1, At, B1); PG8_BAR; PG8_SCHED;
	v_mfma_f32_16x16x32_bf16 v[126:129], v[150:153], v[200:203], v[126:129]
	v_mfma_f32_16x16x32_bf16 v[122:125], v[176:179], v[200:203], v[122:125]
	v_mfma_f32_16x16x32_bf16 v[110:113], v[150:153], v[208:211], v[110:113]
	v_mfma_f32_16x16x32_bf16 v[106:109], v[176:179], v[208:211], v[106:109]
	v_mfma_f32_16x16x32_bf16 v[94:97], v[150:153], v[216:219], v[94:97]
	v_mfma_f32_16x16x32_bf16 v[90:93], v[176:179], v[216:219], v[90:93]
	v_mfma_f32_16x16x32_bf16 v[78:81], v[150:153], v[224:227], v[78:81]
	v_mfma_f32_16x16x32_bf16 v[74:77], v[176:179], v[224:227], v[74:77]
	v_mfma_f32_16x16x32_bf16 v[126:129], v[172:175], v[204:207], v[126:129]
	v_mfma_f32_16x16x32_bf16 v[122:125], v[180:183], v[204:207], v[122:125]
	v_mfma_f32_16x16x32_bf16 v[110:113], v[172:175], v[212:215], v[110:113]
	v_mfma_f32_16x16x32_bf16 v[106:109], v[180:183], v[212:215], v[106:109]
	v_mfma_f32_16x16x32_bf16 v[94:97], v[172:175], v[220:223], v[94:97]
	v_mfma_f32_16x16x32_bf16 v[90:93], v[180:183], v[220:223], v[90:93]
	v_mfma_f32_16x16x32_bf16 v[78:81], v[172:175], v[228:231], v[78:81]
	v_mfma_f32_16x16x32_bf16 v[74:77], v[180:183], v[228:231], v[74:77]
	v_mfma_f32_16x16x32_bf16 v[118:121], v[184:187], v[200:203], v[118:121]
	v_mfma_f32_16x16x32_bf16 v[114:117], v[192:195], v[200:203], v[114:117]
	v_mfma_f32_16x16x32_bf16 v[102:105], v[184:187], v[208:211], v[102:105]
	v_mfma_f32_16x16x32_bf16 v[98:101], v[192:195], v[208:211], v[98:101]
	v_mfma_f32_16x16x32_bf16 v[86:89], v[184:187], v[216:219], v[86:89]
	v_mfma_f32_16x16x32_bf16 v[82:85], v[192:195], v[216:219], v[82:85]
	v_mfma_f32_16x16x32_bf16 v[70:73], v[184:187], v[224:227], v[70:73]
	v_mfma_f32_16x16x32_bf16 v[66:69], v[192:195], v[224:227], v[66:69]
	v_mfma_f32_16x16x32_bf16 v[118:121], v[188:191], v[204:207], v[118:121]
	v_mfma_f32_16x16x32_bf16 v[114:117], v[196:199], v[204:207], v[114:117]
	v_mfma_f32_16x16x32_bf16 v[102:105], v[188:191], v[212:215], v[102:105]
	v_mfma_f32_16x16x32_bf16 v[98:101], v[196:199], v[212:215], v[98:101]
	v_mfma_f32_16x16x32_bf16 v[86:89], v[188:191], v[220:223], v[86:89]
	v_mfma_f32_16x16x32_bf16 v[82:85], v[196:199], v[220:223], v[82:85]
	v_mfma_f32_16x16x32_bf16 v[70:73], v[188:191], v[228:231], v[70:73]
	v_mfma_f32_16x16x32_bf16 v[66:69], v[196:199], v[228:231], v[66:69]
	s_barrier
	s_setprio 0
	s_add_i32 s43, s43, s26
	v_lshl_add_u64 v[144:145], s[22:23], 0, v[134:135]
	s_mov_b32 m0, s43
	ds_read_b128 v[200:203], v148 offset:16384
	ds_read_b128 v[204:207], v148 offset:17408
	ds_read_b128 v[208:211], v148 offset:18432
	ds_read_b128 v[212:215], v148 offset:19456
	ds_read_b128 v[216:219], v148 offset:20480
	ds_read_b128 v[220:223], v148 offset:21504
	ds_read_b128 v[224:227], v148 offset:22528
	ds_read_b128 v[228:231], v148 offset:23552
	global_load_lds_dwordx4 v[144:145], off
	s_add_i32 m0, s43, 0x2000
	s_add_u32 s44, s22, 0x40000
	v_lshl_add_u64 v[232:233], s[22:23], 0, v[130:131]
	s_addc_u32 s45, s23, 0
	s_add_i32 s43, s46, s26
	global_load_lds_dwordx4 v[232:233], off
	v_lshl_add_u64 v[234:235], s[44:45], 0, v[134:135]
	s_mov_b32 m0, s43
	v_lshl_add_u64 v[236:237], s[24:25], 0, v[132:133]
	global_load_lds_dwordx4 v[234:235], off
	v_lshl_add_u64 v[234:235], s[44:45], 0, v[130:131]
	s_add_i32 m0, s43, 0x2000
	s_nop 0
	global_load_lds_dwordx4 v[234:235], off
	v_lshl_add_u64 v[234:235], s[24:25], 0, v[136:137]
	s_mov_b32 m0, s27
	s_nop 0
	global_load_lds_dwordx4 v[234:235], off
	s_mov_b32 m0, s28
	s_nop 0
	global_load_lds_dwordx4 v[236:237], off
	s_waitcnt vmcnt(8)
	s_waitcnt lgkmcnt(0)
	s_setprio 1
	s_barrier
	v_mfma_f32_16x16x32_bf16 v[62:65], v[150:153], v[200:203], v[62:65]
	v_mfma_f32_16x16x32_bf16 v[58:61], v[176:179], v[200:203], v[58:61]
	v_mfma_f32_16x16x32_bf16 v[46:49], v[150:153], v[208:211], v[46:49]
	v_mfma_f32_16x16x32_bf16 v[42:45], v[176:179], v[208:211], v[42:45]
	v_mfma_f32_16x16x32_bf16 v[30:33], v[150:153], v[216:219], v[30:33]
	v_mfma_f32_16x16x32_bf16 v[26:29], v[176:179], v[216:219], v[26:29]
	v_mfma_f32_16x16x32_bf16 v[14:17], v[150:153], v[224:227], v[14:17]
	v_mfma_f32_16x16x32_bf16 v[10:13], v[176:179], v[224:227], v[10:13]
	v_mfma_f32_16x16x32_bf16 v[62:65], v[172:175], v[204:207], v[62:65]
	v_mfma_f32_16x16x32_bf16 v[58:61], v[180:183], v[204:207], v[58:61]
	v_mfma_f32_16x16x32_bf16 v[46:49], v[172:175], v[212:215], v[46:49]
	v_mfma_f32_16x16x32_bf16 v[42:45], v[180:183], v[212:215], v[42:45]
	v_mfma_f32_16x16x32_bf16 v[30:33], v[172:175], v[220:223], v[30:33]
	v_mfma_f32_16x16x32_bf16 v[26:29], v[180:183], v[220:223], v[26:29]
	v_mfma_f32_16x16x32_bf16 v[14:17], v[172:175], v[228:231], v[14:17]
	v_mfma_f32_16x16x32_bf16 v[10:13], v[180:183], v[228:231], v[10:13]
	v_mfma_f32_16x16x32_bf16 v[54:57], v[184:187], v[200:203], v[54:57]
	v_mfma_f32_16x16x32_bf16 v[50:53], v[192:195], v[200:203], v[50:53]
	v_mfma_f32_16x16x32_bf16 v[38:41], v[184:187], v[208:211], v[38:41]
	v_mfma_f32_16x16x32_bf16 v[34:37], v[192:195], v[208:211], v[34:37]
	v_mfma_f32_16x16x32_bf16 v[22:25], v[184:187], v[216:219], v[22:25]
	v_mfma_f32_16x16x32_bf16 v[18:21], v[192:195], v[216:219], v[18:21]
	v_mfma_f32_16x16x32_bf16 v[6:9], v[184:187], v[224:227], v[6:9]
	v_mfma_f32_16x16x32_bf16 v[2:5], v[192:195], v[224:227], v[2:5]
	v_mfma_f32_16x16x32_bf16 v[54:57], v[188:191], v[204:207], v[54:57]
	v_mfma_f32_16x16x32_bf16 v[50:53], v[196:199], v[204:207], v[50:53]
	v_mfma_f32_16x16x32_bf16 v[38:41], v[188:191], v[212:215], v[38:41]
	v_mfma_f32_16x16x32_bf16 v[34:37], v[196:199], v[212:215], v[34:37]
	v_mfma_f32_16x16x32_bf16 v[22:25], v[188:191], v[220:223], v[22:25]
	v_mfma_f32_16x16x32_bf16 v[18:21], v[196:199], v[220:223], v[18:21]
	v_mfma_f32_16x16x32_bf16 v[6:9], v[188:191], v[228:231], v[6:9]
	v_mfma_f32_16x16x32_bf16 v[2:5], v[196:199], v[228:231], v[2:5]
	s_barrier
; #define PG8_STAGE(bufoff, gbase, voff) do { _Pragma("unroll") for (int _i = 0; _i < 2; ++_i) \
;         __builtin_amdgcn_global_load_lds((const unsigned*)((const char*)(gbase) + (voff)[_i]), (PG8_LAS unsigned*)(lds + (bufoff) + ldsw + _i * 8192), 16, 0, 0); } while (0)
; #define PG8_LDA(dst, b, h) do { _Pragma("unroll") for (int m = 0; m < 4; ++m) _Pragma("unroll") for (int k = 0; k < 2; ++k) dst[m][k] = *(const PG8_LAS bf16x8*)(lds + PG8_SA(b, h) + aoff + m * 2048 + k * 1024); } while (0)
; #define PG8_LDB(dst, b, h) do { _Pragma("unroll") for (int n = 0; n < 2; ++n) _Pragma("unroll") for (int k = 0; k < 2; ++k) dst[n][k] = *(const PG8_LAS bf16x8*)(lds + PG8_SB(b, h) + boff + n * 2048 + k * 1024); } while (0)
; #define PG8_MMA(ai, bj, At, Bt) do { __builtin_amdgcn_s_setprio(1); _Pragma("unroll") for (int m = 0; m < 4; ++m) _Pragma("unroll") for (int n = 0; n < 2; ++n) _Pragma("unroll") for (int k = 0; k < 2; ++k) \
;         acc[ai][bj][m][n] = __builtin_amdgcn_mfma_f32_16x16x32_bf16(Bt[n][k], At[m][k], acc[ai][bj][m][n], 0, 0, 0); __builtin_amdgcn_s_setprio(0); } while (0)
; #define PG8_WAIT_V(n) asm volatile("s_waitcnt vmcnt(" #n ")" ::: "memory")
; #define PG8_WAIT_L(n) asm volatile("s_waitcnt lgkmcnt(" #n ")" ::: "memory")
; #define PG8_BAR __builtin_amdgcn_s_barrier()
; #define PG8_SCHED __builtin_amdgcn_sched_barrier(0)
; template <class Epi, class Sched, bool ALIGN_EPI = false, bool SP2 = false>
; __device__ __forceinline__ void gemm_phase(PG8_LAS unsigned char* lds, const Gemm g, const Sched& S, const Epi& E) {
;     ...
;             PG8_LDB(B0, 1, 0); PG8_LDB(B1, 1, 1); PG8_SCHED; PG8_LDA(At, 1, 0); PG8_STAGE(PG8_SA(0, 1), a2 + hstep, voffA);
;             PG8_WAIT_V(8); PG8_WAIT_L(0); PG8_BAR; PG8_MMA(0, 0, At, B0); PG8_MMA(0, 1, At, B1); PG8_BAR; PG8_SCHED;
	s_setprio 0
	s_add_i32 s43, 0, 0x18000
	v_add_u32_e32 v149, s43, v146
	s_add_i32 s44, 0, 0x1c000
	ds_read_b128 v[150:153], v149
	ds_read_b128 v[172:175], v149 offset:1024
	ds_read_b128 v[176:179], v149 offset:2048
	ds_read_b128 v[180:183], v149 offset:3072
	v_add_u32_e32 v149, s44, v146
	ds_read_b128 v[184:187], v149
	ds_read_b128 v[188:191], v149 offset:1024
	ds_read_b128 v[192:195], v149 offset:2048
	ds_read_b128 v[196:199], v149 offset:3072
	s_add_u32 s24, s24, 0x40000
	s_addc_u32 s25, s25, 0
	s_mov_b32 m0, s29
	v_lshl_add_u64 v[238:239], s[24:25], 0, v[136:137]
	ds_read_b128 v[200:203], v148 offset:32768
	ds_read_b128 v[204:207], v148 offset:33792
	ds_read_b128 v[208:211], v148 offset:34816
	ds_read_b128 v[212:215], v148 offset:35840
	ds_read_b128 v[216:219], v148 offset:36864
	ds_read_b128 v[220:223], v148 offset:37888
	ds_read_b128 v[224:227], v148 offset:38912
	ds_read_b128 v[228:231], v148 offset:39936
	global_load_lds_dwordx4 v[238:239], off
	v_lshl_add_u64 v[238:239], s[24:25], 0, v[132:133]
	s_mov_b32 m0, s30
	s_nop 0
	global_load_lds_dwordx4 v[238:239], off
	s_waitcnt vmcnt(8)
	s_waitcnt lgkmcnt(0)
	s_setprio 1
	s_barrier
	v_mfma_f32_16x16x32_bf16 v[126:129], v[150:153], v[200:203], v[126:129]
	v_mfma_f32_16x16x32_bf16 v[122:125], v[176:179], v[200:203], v[122:125]
	v_mfma_f32_16x16x32_bf16 v[110:113], v[150:153], v[208:211], v[110:113]
	v_mfma_f32_16x16x32_bf16 v[106:109], v[176:179], v[208:211], v[106:109]
	v_mfma_f32_16x16x32_bf16 v[94:97], v[150:153], v[216:219], v[94:97]
	v_mfma_f32_16x16x32_bf16 v[90:93], v[176:179], v[216:219], v[90:93]
	v_mfma_f32_16x16x32_bf16 v[78:81], v[150:153], v[224:227], v[78:81]
	v_mfma_f32_16x16x32_bf16 v[74:77], v[176:179], v[224:227], v[74:77]
	v_mfma_f32_16x16x32_bf16 v[126:129], v[172:175], v[204:207], v[126:129]
	v_mfma_f32_16x16x32_bf16 v[122:125], v[180:183], v[204:207], v[122:125]
	v_mfma_f32_16x16x32_bf16 v[110:113], v[172:175], v[212:215], v[110:113]
	v_mfma_f32_16x16x32_bf16 v[106:109], v[180:183], v[212:215], v[106:109]
	v_mfma_f32_16x16x32_bf16 v[94:97], v[172:175], v[220:223], v[94:97]
	v_mfma_f32_16x16x32_bf16 v[90:93], v[180:183], v[220:223], v[90:93]
	v_mfma_f32_16x16x32_bf16 v[78:81], v[172:175], v[228:231], v[78:81]
	v_mfma_f32_16x16x32_bf16 v[74:77], v[180:183], v[228:231], v[74:77]
	v_mfma_f32_16x16x32_bf16 v[118:121], v[184:187], v[200:203], v[118:121]
	v_mfma_f32_16x16x32_bf16 v[114:117], v[192:195], v[200:203], v[114:117]
	v_mfma_f32_16x16x32_bf16 v[102:105], v[184:187], v[208:211], v[102:105]
	v_mfma_f32_16x16x32_bf16 v[98:101], v[192:195], v[208:211], v[98:101]
	v_mfma_f32_16x16x32_bf16 v[86:89], v[184:187], v[216:219], v[86:89]
	v_mfma_f32_16x16x32_bf16 v[82:85], v[192:195], v[216:219], v[82:85]
	v_mfma_f32_16x16x32_bf16 v[70:73], v[184:187], v[224:227], v[70:73]
	v_mfma_f32_16x16x32_bf16 v[66:69], v[192:195], v[224:227], v[66:69]
	v_mfma_f32_16x16x32_bf16 v[118:121], v[188:191], v[204:207], v[118:121]
	v_mfma_f32_16x16x32_bf16 v[114:117], v[196:199], v[204:207], v[114:117]
	v_mfma_f32_16x16x32_bf16 v[102:105], v[188:191], v[212:215], v[102:105]
	v_mfma_f32_16x16x32_bf16 v[98:101], v[196:199], v[212:215], v[98:101]
	v_mfma_f32_16x16x32_bf16 v[86:89], v[188:191], v[220:223], v[86:89]
	v_mfma_f32_16x16x32_bf16 v[82:85], v[196:199], v[220:223], v[82:85]
	v_mfma_f32_16x16x32_bf16 v[70:73], v[188:191], v[228:231], v[70:73]
	v_mfma_f32_16x16x32_bf16 v[66:69], v[196:199], v[228:231], v[66:69]
	s_barrier
; #define PG8_STAGE(bufoff, gbase, voff) do { _Pragma("unroll") for (int _i = 0; _i < 2; ++_i) \
;         __builtin_amdgcn_global_load_lds((const unsigned*)((const char*)(gbase) + (voff)[_i]), (PG8_LAS unsigned*)(lds + (bufoff) + ldsw + _i * 8192), 16, 0, 0); } while (0)
; #define PG8_LDA(dst, b, h) do { _Pragma("unroll") for (int m = 0; m < 4; ++m) _Pragma("unroll") for (int k = 0; k < 2; ++k) dst[m][k] = *(const PG8_LAS bf16x8*)(lds + PG8_SA(b, h) + aoff + m * 2048 + k * 1024); } while (0)
; #define PG8_MMA(ai, bj, At, Bt) do { __builtin_amdgcn_s_setprio(1); _Pragma("unroll") for (int m = 0; m < 4; ++m) _Pragma("unroll") for (int n = 0; n < 2; ++n) _Pragma("unroll") for (int k = 0; k < 2; ++k) \
;         acc[ai][bj][m][n] = __builtin_amdgcn_mfma_f32_16x16x32_bf16(Bt[n][k], At[m][k], acc[ai][bj][m][n], 0, 0, 0); __builtin_amdgcn_s_setprio(0); } while (0)
; #define PG8_WAIT_V(n) asm volatile("s_waitcnt vmcnt(" #n ")" ::: "memory")
; #define PG8_WAIT_L(n) asm volatile("s_waitcnt lgkmcnt(" #n ")" ::: "memory")
; #define PG8_BAR __builtin_amdgcn_s_barrier()
; #define PG8_SCHED __builtin_amdgcn_sched_barrier(0)
; template <class Epi, class Sched, bool ALIGN_EPI = false, bool SP2 = false>
; __device__ __forceinline__ void gemm_phase(PG8_LAS unsigned char* lds, const Gemm g, const Sched& S, const Epi& E) {
;     ...
;             PG8_LDA(At, 1, 1); PG8_STAGE(PG8_SB(1, 0), b3, voffB); PG8_STAGE(PG8_SB(1, 1), b3 + hstep, voffB); PG8_STAGE(PG8_SA(1, 0), a3, voffA);
;             PG8_WAIT_V(8); PG8_WAIT_L(0); PG8_BAR; PG8_MMA(1, 0, At, B0); PG8_MMA(1, 1, At, B1); PG8_BAR; PG8_SCHED;
	s_setprio 0
	s_add_i32 s24, s43, s26
	v_lshl_add_u64 v[144:145], v[144:145], 0, s[86:87]
	s_mov_b32 m0, s24
	ds_read_b128 v[200:203], v148 offset:49152
	ds_read_b128 v[204:207], v148 offset:50176
	ds_read_b128 v[208:211], v148 offset:51200
	ds_read_b128 v[212:215], v148 offset:52224
	ds_read_b128 v[216:219], v148 offset:53248
	ds_read_b128 v[220:223], v148 offset:54272
	ds_read_b128 v[224:227], v148 offset:55296
	ds_read_b128 v[228:231], v148 offset:56320
	global_load_lds_dwordx4 v[144:145], off
	s_add_i32 m0, s24, 0x2000
	s_add_u32 s22, s22, 0x40080
	v_lshl_add_u64 v[144:145], v[232:233], 0, s[86:87]
	s_addc_u32 s23, s23, 0
	s_add_i32 s24, s44, s26
	global_load_lds_dwordx4 v[144:145], off
	v_lshl_add_u64 v[144:145], s[22:23], 0, v[134:135]
	s_mov_b32 m0, s24
	s_nop 0
	global_load_lds_dwordx4 v[144:145], off
	v_lshl_add_u64 v[144:145], s[22:23], 0, v[130:131]
	s_add_i32 m0, s24, 0x2000
	s_nop 0
	global_load_lds_dwordx4 v[144:145], off
	v_lshl_add_u64 v[144:145], v[234:235], 0, s[86:87]
	s_mov_b32 m0, s31
	s_nop 0
	global_load_lds_dwordx4 v[144:145], off
	v_lshl_add_u64 v[144:145], v[236:237], 0, s[86:87]
	s_mov_b32 m0, s34
	s_nop 0
	global_load_lds_dwordx4 v[144:145], off
	s_waitcnt vmcnt(8)
	s_waitcnt lgkmcnt(0)
	s_setprio 1
	s_barrier
	v_mfma_f32_16x16x32_bf16 v[62:65], v[150:153], v[200:203], v[62:65]
	v_mfma_f32_16x16x32_bf16 v[58:61], v[176:179], v[200:203], v[58:61]
	v_mfma_f32_16x16x32_bf16 v[46:49], v[150:153], v[208:211], v[46:49]
	v_mfma_f32_16x16x32_bf16 v[42:45], v[176:179], v[208:211], v[42:45]
	v_mfma_f32_16x16x32_bf16 v[30:33], v[150:153], v[216:219], v[30:33]
	v_mfma_f32_16x16x32_bf16 v[26:29], v[176:179], v[216:219], v[26:29]
	v_mfma_f32_16x16x32_bf16 v[14:17], v[150:153], v[224:227], v[14:17]
	v_mfma_f32_16x16x32_bf16 v[10:13], v[176:179], v[224:227], v[10:13]
	v_mfma_f32_16x16x32_bf16 v[62:65], v[172:175], v[204:207], v[62:65]
	v_mfma_f32_16x16x32_bf16 v[58:61], v[180:183], v[204:207], v[58:61]
	v_mfma_f32_16x16x32_bf16 v[46:49], v[172:175], v[212:215], v[46:49]
	v_mfma_f32_16x16x32_bf16 v[42:45], v[180:183], v[212:215], v[42:45]
	v_mfma_f32_16x16x32_bf16 v[30:33], v[172:175], v[220:223], v[30:33]
	v_mfma_f32_16x16x32_bf16 v[26:29], v[180:183], v[220:223], v[26:29]
	v_mfma_f32_16x16x32_bf16 v[14:17], v[172:175], v[228:231], v[14:17]
	v_mfma_f32_16x16x32_bf16 v[10:13], v[180:183], v[228:231], v[10:13]
	v_mfma_f32_16x16x32_bf16 v[54:57], v[184:187], v[200:203], v[54:57]
	v_mfma_f32_16x16x32_bf16 v[50:53], v[192:195], v[200:203], v[50:53]
	v_mfma_f32_16x16x32_bf16 v[38:41], v[184:187], v[208:211], v[38:41]
	v_mfma_f32_16x16x32_bf16 v[34:37], v[192:195], v[208:211], v[34:37]
	v_mfma_f32_16x16x32_bf16 v[22:25], v[184:187], v[216:219], v[22:25]
	v_mfma_f32_16x16x32_bf16 v[18:21], v[192:195], v[216:219], v[18:21]
	v_mfma_f32_16x16x32_bf16 v[6:9], v[184:187], v[224:227], v[6:9]
	v_mfma_f32_16x16x32_bf16 v[2:5], v[192:195], v[224:227], v[2:5]
	v_mfma_f32_16x16x32_bf16 v[54:57], v[188:191], v[204:207], v[54:57]
	v_mfma_f32_16x16x32_bf16 v[50:53], v[196:199], v[204:207], v[50:53]
	v_mfma_f32_16x16x32_bf16 v[38:41], v[188:191], v[212:215], v[38:41]
	v_mfma_f32_16x16x32_bf16 v[34:37], v[196:199], v[212:215], v[34:37]
	v_mfma_f32_16x16x32_bf16 v[22:25], v[188:191], v[220:223], v[22:25]
	v_mfma_f32_16x16x32_bf16 v[18:21], v[196:199], v[220:223], v[18:21]
	v_mfma_f32_16x16x32_bf16 v[6:9], v[188:191], v[228:231], v[6:9]
	v_mfma_f32_16x16x32_bf16 v[2:5], v[196:199], v[228:231], v[2:5]
	s_barrier
	s_setprio 0
	s_add_i32 s42, s42, 2
	s_add_u32 s20, s20, 0x100
	s_addc_u32 s21, s21, 0
	s_add_u32 s40, s40, 0x100
	s_addc_u32 s41, s41, 0
	s_cmp_gt_u32 s42, 13
	s_cbranch_scc0 .LBB0_284
